# gemm_small: K permuted inside 64-element blocks so each 128B line is read by back-to-back loads
# baseline (speedup 1.0000x reference)
.LBB0_468:
	v_mov_b32_e32 v5, v0
	s_and_b32 s24, s12, 0x380
	s_and_b32 s8, s10, -16
	v_ashrrev_i32_e32 v100, 6, v5
	v_and_b32_e32 v4, 15, v5
	v_lshlrev_b32_e32 v6, 7, v100
	v_or_b32_e32 v2, s24, v4
	v_ashrrev_i32_e32 v7, 31, v6
	v_lshlrev_b32_e32 v2, 11, v2
	v_lshl_add_u64 v[8:9], s[4:5], 0, v[2:3]
	v_lshlrev_b64 v[6:7], 1, v[6:7]
	v_lshl_add_u64 v[8:9], v[8:9], 0, v[6:7]
	v_and_b32_e32 v2, 48, v5
	v_lshlrev_b32_e32 v2, 1, v2
	v_lshl_add_u64 v[84:85], v[8:9], 0, v[2:3]
	v_add_co_u32_e32 v86, vcc, s16, v84
	s_addk_i32 s8, 0x4000
	s_nop 0
	v_addc_co_u32_e32 v87, vcc, 0, v85, vcc
	v_add_co_u32_e32 v88, vcc, s17, v84
	v_or_b32_e32 v101, s8, v4
	s_nop 0
	v_addc_co_u32_e32 v89, vcc, 0, v85, vcc
	v_add_co_u32_e32 v90, vcc, s18, v84
	v_mov_b64_e32 v[10:11], s[2:3]
	s_nop 0
	v_addc_co_u32_e32 v91, vcc, 0, v85, vcc
	v_add_co_u32_e32 v92, vcc, s19, v84
	v_mad_i64_i32 v[10:11], s[8:9], v101, s14, v[10:11]
	s_nop 0
	v_addc_co_u32_e32 v93, vcc, 0, v85, vcc
	v_add_co_u32_e32 v94, vcc, s20, v84
	v_lshl_add_u64 v[6:7], v[10:11], 0, v[6:7]
	s_nop 0
	v_addc_co_u32_e32 v95, vcc, 0, v85, vcc
	v_add_co_u32_e32 v96, vcc, s21, v84
	v_lshl_add_u64 v[82:83], v[6:7], 0, v[2:3]
	s_nop 0
	v_addc_co_u32_e32 v97, vcc, 0, v85, vcc
	global_load_dwordx4 v[6:9], v[82:83], off
	global_load_dwordx4 v[10:13], v[84:85], off
	global_load_dwordx4 v[14:17], v[86:87], off
	global_load_dwordx4 v[18:21], v[88:89], off
	global_load_dwordx4 v[22:25], v[90:91], off
	global_load_dwordx4 v[26:29], v[92:93], off
	global_load_dwordx4 v[30:33], v[94:95], off
	global_load_dwordx4 v[34:37], v[96:97], off
	v_add_co_u32_e32 v98, vcc, s22, v84
	v_lshlrev_b32_e32 v2, 4, v100
	s_nop 0
	v_addc_co_u32_e32 v99, vcc, 0, v85, vcc
	global_load_dwordx4 v[38:41], v[98:99], off
	global_load_dwordx4 v[42:45], v[84:85], off offset:16
	global_load_dwordx4 v[46:49], v[82:83], off offset:16
	global_load_dwordx4 v[50:53], v[86:87], off offset:16
	global_load_dwordx4 v[54:57], v[88:89], off offset:16
	global_load_dwordx4 v[58:61], v[90:91], off offset:16
	global_load_dwordx4 v[62:65], v[92:93], off offset:16
	global_load_dwordx4 v[66:69], v[94:95], off offset:16
	global_load_dwordx4 v[70:73], v[96:97], off offset:16
	global_load_dwordx4 v[74:77], v[98:99], off offset:16
	s_waitcnt vmcnt(16)
	v_mfma_f32_16x16x32_bf16 v[10:13], v[10:13], v[6:9], 0
	s_waitcnt vmcnt(15)
	v_mfma_f32_16x16x32_bf16 v[14:17], v[14:17], v[6:9], 0
	s_waitcnt vmcnt(14)
	v_mfma_f32_16x16x32_bf16 v[18:21], v[18:21], v[6:9], 0
	s_waitcnt vmcnt(13)
	v_mfma_f32_16x16x32_bf16 v[22:25], v[22:25], v[6:9], 0
	s_waitcnt vmcnt(12)
	v_mfma_f32_16x16x32_bf16 v[26:29], v[26:29], v[6:9], 0
	s_waitcnt vmcnt(11)
	v_mfma_f32_16x16x32_bf16 v[30:33], v[30:33], v[6:9], 0
	s_waitcnt vmcnt(10)
	v_mfma_f32_16x16x32_bf16 v[34:37], v[34:37], v[6:9], 0
	s_waitcnt vmcnt(9)
	v_mfma_f32_16x16x32_bf16 v[6:9], v[38:41], v[6:9], 0
	global_load_dwordx4 v[38:41], v[84:85], off offset:128
	global_load_dwordx4 v[78:81], v[82:83], off offset:128
	s_waitcnt vmcnt(9)
	v_mfma_f32_16x16x32_bf16 v[10:13], v[42:45], v[46:49], v[10:13]
	global_load_dwordx4 v[42:45], v[86:87], off offset:128
	s_waitcnt vmcnt(9)
	v_mfma_f32_16x16x32_bf16 v[14:17], v[50:53], v[46:49], v[14:17]
	global_load_dwordx4 v[50:53], v[88:89], off offset:128
	s_waitcnt vmcnt(7)
	v_mfma_f32_16x16x32_bf16 v[26:29], v[62:65], v[46:49], v[26:29]
	global_load_dwordx4 v[62:65], v[94:95], off offset:128
	s_waitcnt vmcnt(7)
	v_mfma_f32_16x16x32_bf16 v[30:33], v[66:69], v[46:49], v[30:33]
	global_load_dwordx4 v[66:69], v[96:97], off offset:128
	v_mfma_f32_16x16x32_bf16 v[18:21], v[54:57], v[46:49], v[18:21]
	global_load_dwordx4 v[54:57], v[90:91], off offset:128
	v_mfma_f32_16x16x32_bf16 v[22:25], v[58:61], v[46:49], v[22:25]
	global_load_dwordx4 v[58:61], v[92:93], off offset:128
	s_waitcnt vmcnt(9)
	v_mfma_f32_16x16x32_bf16 v[34:37], v[70:73], v[46:49], v[34:37]
	global_load_dwordx4 v[70:73], v[98:99], off offset:128
	s_waitcnt vmcnt(9)
	v_mfma_f32_16x16x32_bf16 v[6:9], v[74:77], v[46:49], v[6:9]
	global_load_dwordx4 v[46:49], v[84:85], off offset:144
	global_load_dwordx4 v[74:77], v[82:83], off offset:144
	s_waitcnt vmcnt(9)
	v_mfma_f32_16x16x32_bf16 v[10:13], v[38:41], v[78:81], v[10:13]
	global_load_dwordx4 v[38:41], v[86:87], off offset:144
	s_waitcnt vmcnt(9)
	v_mfma_f32_16x16x32_bf16 v[14:17], v[42:45], v[78:81], v[14:17]
	global_load_dwordx4 v[42:45], v[88:89], off offset:144
	s_waitcnt vmcnt(9)
	v_mfma_f32_16x16x32_bf16 v[18:21], v[50:53], v[78:81], v[18:21]
	global_load_dwordx4 v[50:53], v[90:91], off offset:144
	s_waitcnt vmcnt(8)
	v_mfma_f32_16x16x32_bf16 v[34:37], v[66:69], v[78:81], v[34:37]
	global_load_dwordx4 v[66:69], v[98:99], off offset:144
	s_waitcnt vmcnt(8)
	v_mfma_f32_16x16x32_bf16 v[22:25], v[54:57], v[78:81], v[22:25]
	global_load_dwordx4 v[54:57], v[92:93], off offset:144
	s_waitcnt vmcnt(8)
	v_mfma_f32_16x16x32_bf16 v[26:29], v[58:61], v[78:81], v[26:29]
	global_load_dwordx4 v[58:61], v[94:95], off offset:144
	v_mfma_f32_16x16x32_bf16 v[30:33], v[62:65], v[78:81], v[30:33]
	global_load_dwordx4 v[62:65], v[96:97], off offset:144
	s_waitcnt vmcnt(6)
	v_mfma_f32_16x16x32_bf16 v[14:17], v[38:41], v[74:77], v[14:17]
	v_add_u32_e32 v38, s24, v2
	v_lshrrev_b32_e32 v39, 2, v5
	v_and_or_b32 v38, v39, 12, v38
	v_mov_b64_e32 v[40:41], s[60:61]
	v_mad_i64_i32 v[40:41], s[8:9], v101, s14, v[40:41]
	v_ashrrev_i32_e32 v39, 31, v38
	s_waitcnt vmcnt(5)
	v_mfma_f32_16x16x32_bf16 v[18:21], v[42:45], v[74:77], v[18:21]
	v_lshl_add_u64 v[42:43], v[38:39], 1, v[40:41]
	v_add_co_u32_e32 v40, vcc, s15, v42
	v_lshl_add_u64 v[38:39], v[38:39], 2, s[62:63]
	s_nop 0
	v_addc_co_u32_e32 v41, vcc, 0, v43, vcc
	v_mfma_f32_16x16x32_bf16 v[10:13], v[46:49], v[74:77], v[10:13]
	global_load_dwordx2 v[44:45], v[40:41], off offset:3072
	global_load_dwordx2 v[46:47], v[42:43], off offset:2048
	v_and_b32_e32 v48, 63, v5
	global_load_dwordx4 v[38:41], v[38:39], off
	v_mfma_f32_16x16x32_bf16 v[6:9], v[70:73], v[78:81], v[6:9]
	v_lshlrev_b32_e32 v49, 13, v100
	v_lshl_add_u32 v5, v5, 4, 0
	s_waitcnt vmcnt(7)
	v_mfma_f32_16x16x32_bf16 v[22:25], v[50:53], v[74:77], v[22:25]
	v_lshlrev_b32_e32 v50, 4, v48
	v_add3_u32 v49, 0, v49, v50
	s_barrier
	s_waitcnt vmcnt(6)
	v_mfma_f32_16x16x32_bf16 v[6:9], v[66:69], v[74:77], v[6:9]
	v_cmp_gt_u32_e32 vcc, 16, v48
	s_waitcnt vmcnt(5)
	v_mfma_f32_16x16x32_bf16 v[26:29], v[54:57], v[74:77], v[26:29]
	s_waitcnt vmcnt(4)
	v_mfma_f32_16x16x32_bf16 v[30:33], v[58:61], v[74:77], v[30:33]
	s_waitcnt vmcnt(3)
	v_mfma_f32_16x16x32_bf16 v[34:37], v[62:65], v[74:77], v[34:37]
	ds_write_b128 v49, v[10:13]
	ds_write_b128 v49, v[14:17] offset:1024
	ds_write_b128 v49, v[18:21] offset:2048
	ds_write_b128 v49, v[22:25] offset:3072
	ds_write_b128 v49, v[26:29] offset:4096
	s_nop 0
	ds_write_b128 v49, v[30:33] offset:5120
	s_nop 0
	ds_write_b128 v49, v[34:37] offset:6144
	ds_write_b128 v49, v[6:9] offset:7168
	s_waitcnt lgkmcnt(0)
	s_barrier
	ds_read_b128 v[6:9], v5
	ds_read_b128 v[10:13], v5 offset:8192
	ds_read_b128 v[14:17], v5 offset:16384
	s_waitcnt lgkmcnt(2)
	v_pk_add_f32 v[8:9], v[8:9], 0 op_sel_hi:[1,0]
	v_pk_add_f32 v[18:19], v[6:7], 0 op_sel_hi:[1,0]
	s_waitcnt lgkmcnt(1)
	v_pk_add_f32 v[12:13], v[8:9], v[12:13]
	ds_read_b128 v[6:9], v5 offset:24576
	v_pk_add_f32 v[18:19], v[18:19], v[10:11]
	s_waitcnt lgkmcnt(1)
	v_pk_add_f32 v[16:17], v[12:13], v[16:17]
	ds_read_b128 v[10:13], v5 offset:32768
	v_pk_add_f32 v[14:15], v[18:19], v[14:15]
	s_waitcnt lgkmcnt(1)
	v_pk_add_f32 v[16:17], v[16:17], v[8:9]
	v_pk_add_f32 v[18:19], v[14:15], v[6:7]
	ds_read_b128 v[6:9], v5 offset:40960
	s_waitcnt lgkmcnt(1)
	v_pk_add_f32 v[20:21], v[16:17], v[12:13]
	ds_read_b128 v[12:15], v5 offset:49152
	v_pk_add_f32 v[10:11], v[18:19], v[10:11]
	ds_read_b128 v[16:19], v5 offset:57344
	s_waitcnt lgkmcnt(2)
	v_pk_add_f32 v[6:7], v[10:11], v[6:7]
	v_pk_add_f32 v[8:9], v[20:21], v[8:9]
	s_waitcnt lgkmcnt(1)
	v_pk_add_f32 v[6:7], v[6:7], v[12:13]
	v_pk_add_f32 v[8:9], v[8:9], v[14:15]
	s_waitcnt lgkmcnt(0)
	v_pk_add_f32 v[6:7], v[6:7], v[16:17]
	v_pk_add_f32 v[8:9], v[8:9], v[18:19]
	s_waitcnt vmcnt(2)
	v_lshlrev_b32_e32 v5, 16, v44
	s_waitcnt vmcnt(1)
	v_lshlrev_b32_e32 v12, 16, v46
	v_and_b32_e32 v13, 0xffff0000, v46
	s_waitcnt vmcnt(0)
	v_add_f32_e32 v6, v38, v6
	v_mul_f32_e32 v6, 0xbfb8aa3b, v6
	v_exp_f32_e32 v11, v6
	v_mul_f32_e32 v6, 0xbfb8aa3b, v12
	v_exp_f32_e32 v10, v6
	v_add_f32_e32 v6, v39, v7
	v_mul_f32_e32 v6, 0xbfb8aa3b, v6
	v_exp_f32_e32 v7, v6
	v_mul_f32_e32 v6, 0xbfb8aa3b, v13
	v_exp_f32_e32 v6, v6
	v_pk_add_f32 v[10:11], v[10:11], 1.0 op_sel_hi:[1,0]
	v_pk_add_f32 v[6:7], v[6:7], 1.0 op_sel_hi:[1,0]
	v_mul_f32_e32 v10, v10, v11
	v_rcp_f32_e32 v10, v10
	v_mul_f32_e32 v6, v6, v7
	v_rcp_f32_e32 v6, v6
	v_lshlrev_b32_e32 v11, 16, v45
	v_mul_f32_e32 v7, v10, v12
	v_mul_f32_e32 v5, v7, v5
	v_and_b32_e32 v7, 0xffff0000, v44
	v_mul_f32_e32 v6, v6, v13
	v_mul_f32_e32 v10, v6, v7
	v_add_f32_e32 v6, v40, v8
	v_lshlrev_b32_e32 v12, 16, v47
	v_mul_f32_e32 v6, 0xbfb8aa3b, v6
	v_exp_f32_e32 v7, v6
	v_mul_f32_e32 v6, 0xbfb8aa3b, v12
	v_add_f32_e32 v8, v41, v9
	v_exp_f32_e32 v6, v6
	v_and_b32_e32 v13, 0xffff0000, v47
	v_mul_f32_e32 v8, 0xbfb8aa3b, v8
	v_exp_f32_e32 v9, v8
	v_mul_f32_e32 v8, 0xbfb8aa3b, v13
	v_exp_f32_e32 v8, v8
	v_pk_add_f32 v[6:7], v[6:7], 1.0 op_sel_hi:[1,0]
	s_nop 0
	v_mul_f32_e32 v6, v6, v7
	v_rcp_f32_e32 v14, v6
	v_pk_add_f32 v[6:7], v[8:9], 1.0 op_sel_hi:[1,0]
	v_and_b32_e32 v8, 0xffff0000, v45
	v_mul_f32_e32 v6, v6, v7
	v_rcp_f32_e32 v6, v6
	v_mul_f32_e32 v7, v14, v12
	v_mul_f32_e32 v7, v7, v11
	v_mul_f32_e32 v6, v6, v13
	v_mul_f32_e32 v8, v6, v8
	v_cvt_pk_bf16_f32 v6, v5, v10
	v_cvt_pk_bf16_f32 v7, v7, v8
	global_store_dwordx2 v[42:43], v[6:7], off offset:2048
	s_barrier
	s_and_saveexec_b64 s[8:9], vcc
	s_cbranch_execz .LBB0_467
	v_lshlrev_b32_e32 v2, 2, v2
	v_lshlrev_b32_e32 v4, 2, v4
	v_add3_u32 v2, 0, v2, v4
	ds_write_b32 v2, v3
	s_branch .LBB0_467

.LBB0_603:
	v_mov_b32_e32 v16, v0
	s_and_b32 s14, s18, 0x380
	s_and_b32 s12, s16, -16
	v_ashrrev_i32_e32 v124, 6, v16
	v_and_b32_e32 v17, 15, v16
	s_waitcnt vmcnt(10)
	v_lshlrev_b32_e32 v18, 8, v124
	v_or_b32_e32 v2, s14, v17
	v_ashrrev_i32_e32 v19, 31, v18
	v_lshlrev_b32_e32 v2, 12, v2
	v_lshl_add_u64 v[20:21], s[4:5], 0, v[2:3]
	v_lshlrev_b64 v[22:23], 1, v[18:19]
	v_lshl_add_u64 v[18:19], v[20:21], 0, v[22:23]
	v_and_b32_e32 v2, 48, v16
	v_lshlrev_b32_e32 v2, 1, v2
	v_lshl_add_u64 v[106:107], v[18:19], 0, v[2:3]
	v_add_co_u32_e32 v110, vcc, s22, v106
	s_addk_i32 s12, 0x4000
	s_nop 0
	v_addc_co_u32_e32 v111, vcc, 0, v107, vcc
	v_add_co_u32_e32 v112, vcc, s23, v106
	v_or_b32_e32 v6, s12, v17
	s_nop 0
	v_addc_co_u32_e32 v113, vcc, 0, v107, vcc
	v_add_co_u32_e32 v114, vcc, s24, v106
	global_load_dwordx4 v[18:21], v[106:107], off
	s_nop 0
	v_addc_co_u32_e32 v115, vcc, 0, v107, vcc
	v_add_co_u32_e32 v116, vcc, s25, v106
	v_mad_i64_i32 v[24:25], s[30:31], v6, s21, v[4:5]
	s_nop 0
	v_addc_co_u32_e32 v117, vcc, 0, v107, vcc
	v_add_co_u32_e32 v118, vcc, s26, v106
	global_load_dwordx4 v[26:29], v[110:111], off
	global_load_dwordx4 v[30:33], v[112:113], off
	v_addc_co_u32_e32 v119, vcc, 0, v107, vcc
	v_add_co_u32_e32 v120, vcc, s27, v106
	v_lshl_add_u64 v[22:23], v[24:25], 0, v[22:23]
	s_nop 0
	v_addc_co_u32_e32 v121, vcc, 0, v107, vcc
	global_load_dwordx4 v[34:37], v[114:115], off
	global_load_dwordx4 v[38:41], v[116:117], off
	global_load_dwordx4 v[42:45], v[118:119], off
	global_load_dwordx4 v[46:49], v[120:121], off
	v_lshl_add_u64 v[108:109], v[22:23], 0, v[2:3]
	global_load_dwordx4 v[22:25], v[108:109], off
	v_add_co_u32_e32 v122, vcc, s28, v106
	v_lshlrev_b32_e32 v2, 4, v124
	s_nop 0
	v_addc_co_u32_e32 v123, vcc, 0, v107, vcc
	global_load_dwordx4 v[50:53], v[122:123], off
	global_load_dwordx4 v[54:57], v[106:107], off offset:16
	global_load_dwordx4 v[58:61], v[108:109], off offset:16
	global_load_dwordx4 v[62:65], v[110:111], off offset:16
	global_load_dwordx4 v[66:69], v[112:113], off offset:16
	global_load_dwordx4 v[70:73], v[114:115], off offset:16
	global_load_dwordx4 v[74:77], v[116:117], off offset:16
	global_load_dwordx4 v[78:81], v[118:119], off offset:16
	global_load_dwordx4 v[82:85], v[120:121], off offset:16
	global_load_dwordx4 v[86:89], v[122:123], off offset:16
	global_load_dwordx4 v[90:93], v[106:107], off offset:128
	global_load_dwordx4 v[94:97], v[108:109], off offset:128
	v_ashrrev_i32_e32 v7, 31, v6
	v_cmp_gt_i32_e32 vcc, s20, v6
	s_waitcnt vmcnt(12)
	v_mfma_f32_16x16x32_bf16 v[18:21], v[18:21], v[22:25], 0
	v_mfma_f32_16x16x32_bf16 v[26:29], v[26:29], v[22:25], 0
	v_mfma_f32_16x16x32_bf16 v[30:33], v[30:33], v[22:25], 0
	v_mfma_f32_16x16x32_bf16 v[34:37], v[34:37], v[22:25], 0
	v_mfma_f32_16x16x32_bf16 v[38:41], v[38:41], v[22:25], 0
	v_mfma_f32_16x16x32_bf16 v[42:45], v[42:45], v[22:25], 0
	v_mfma_f32_16x16x32_bf16 v[46:49], v[46:49], v[22:25], 0
	s_waitcnt vmcnt(11)
	v_mfma_f32_16x16x32_bf16 v[22:25], v[50:53], v[22:25], 0
	global_load_dwordx4 v[50:53], v[110:111], off offset:128
	s_waitcnt vmcnt(10)
	v_mfma_f32_16x16x32_bf16 v[18:21], v[54:57], v[58:61], v[18:21]
	global_load_dwordx4 v[54:57], v[112:113], off offset:128
	s_waitcnt vmcnt(10)
	v_mfma_f32_16x16x32_bf16 v[26:29], v[62:65], v[58:61], v[26:29]
	global_load_dwordx4 v[62:65], v[114:115], off offset:128
	s_waitcnt vmcnt(10)
	v_mfma_f32_16x16x32_bf16 v[30:33], v[66:69], v[58:61], v[30:33]
	global_load_dwordx4 v[66:69], v[116:117], off offset:128
	s_waitcnt vmcnt(10)
	v_mfma_f32_16x16x32_bf16 v[34:37], v[70:73], v[58:61], v[34:37]
	global_load_dwordx4 v[70:73], v[118:119], off offset:128
	s_waitcnt vmcnt(10)
	v_mfma_f32_16x16x32_bf16 v[38:41], v[74:77], v[58:61], v[38:41]
	global_load_dwordx4 v[74:77], v[120:121], off offset:128
	s_waitcnt vmcnt(10)
	v_mfma_f32_16x16x32_bf16 v[42:45], v[78:81], v[58:61], v[42:45]
	global_load_dwordx4 v[78:81], v[122:123], off offset:128
	s_waitcnt vmcnt(10)
	v_mfma_f32_16x16x32_bf16 v[46:49], v[82:85], v[58:61], v[46:49]
	global_load_dwordx4 v[82:85], v[106:107], off offset:144
	global_load_dwordx4 v[98:101], v[108:109], off offset:144
	s_waitcnt vmcnt(11)
	v_mfma_f32_16x16x32_bf16 v[22:25], v[86:89], v[58:61], v[22:25]
	global_load_dwordx4 v[58:61], v[110:111], off offset:144
	global_load_dwordx4 v[86:89], v[112:113], off offset:144
	s_waitcnt vmcnt(10)
	v_mfma_f32_16x16x32_bf16 v[26:29], v[50:53], v[94:97], v[26:29]
	global_load_dwordx4 v[50:53], v[114:115], off offset:144
	s_waitcnt vmcnt(10)
	v_mfma_f32_16x16x32_bf16 v[30:33], v[54:57], v[94:97], v[30:33]
	global_load_dwordx4 v[54:57], v[116:117], off offset:144
	s_waitcnt vmcnt(10)
	v_mfma_f32_16x16x32_bf16 v[34:37], v[62:65], v[94:97], v[34:37]
	global_load_dwordx4 v[62:65], v[118:119], off offset:144
	s_waitcnt vmcnt(10)
	v_mfma_f32_16x16x32_bf16 v[38:41], v[66:69], v[94:97], v[38:41]
	global_load_dwordx4 v[66:69], v[120:121], off offset:144
	v_mfma_f32_16x16x32_bf16 v[18:21], v[90:93], v[94:97], v[18:21]
	s_waitcnt vmcnt(10)
	v_mfma_f32_16x16x32_bf16 v[42:45], v[70:73], v[94:97], v[42:45]
	global_load_dwordx4 v[70:73], v[122:123], off offset:144
	global_load_dwordx4 v[90:93], v[106:107], off offset:256
	s_waitcnt vmcnt(11)
	v_mfma_f32_16x16x32_bf16 v[46:49], v[74:77], v[94:97], v[46:49]
	global_load_dwordx4 v[74:77], v[108:109], off offset:256
	global_load_dwordx4 v[102:105], v[110:111], off offset:256
	s_waitcnt vmcnt(12)
	v_mfma_f32_16x16x32_bf16 v[22:25], v[78:81], v[94:97], v[22:25]
	global_load_dwordx4 v[78:81], v[112:113], off offset:256
	s_waitcnt vmcnt(11)
	v_mfma_f32_16x16x32_bf16 v[18:21], v[82:85], v[98:101], v[18:21]
	global_load_dwordx4 v[82:85], v[114:115], off offset:256
	s_waitcnt vmcnt(11)
	v_mfma_f32_16x16x32_bf16 v[26:29], v[58:61], v[98:101], v[26:29]
	global_load_dwordx4 v[58:61], v[116:117], off offset:256
	s_waitcnt vmcnt(11)
	v_mfma_f32_16x16x32_bf16 v[30:33], v[86:89], v[98:101], v[30:33]
	global_load_dwordx4 v[86:89], v[118:119], off offset:256
	s_waitcnt vmcnt(11)
	v_mfma_f32_16x16x32_bf16 v[34:37], v[50:53], v[98:101], v[34:37]
	global_load_dwordx4 v[50:53], v[120:121], off offset:256
	s_waitcnt vmcnt(11)
	v_mfma_f32_16x16x32_bf16 v[38:41], v[54:57], v[98:101], v[38:41]
	global_load_dwordx4 v[54:57], v[122:123], off offset:256
	s_waitcnt vmcnt(11)
	v_mfma_f32_16x16x32_bf16 v[42:45], v[62:65], v[98:101], v[42:45]
	global_load_dwordx4 v[62:65], v[106:107], off offset:272
	s_waitcnt vmcnt(11)
	v_mfma_f32_16x16x32_bf16 v[46:49], v[66:69], v[98:101], v[46:49]
	global_load_dwordx4 v[66:69], v[108:109], off offset:272
	global_load_dwordx4 v[94:97], v[110:111], off offset:272
	s_waitcnt vmcnt(12)
	v_mfma_f32_16x16x32_bf16 v[22:25], v[70:73], v[98:101], v[22:25]
	global_load_dwordx4 v[70:73], v[112:113], off offset:272
	global_load_dwordx4 v[98:101], v[116:117], off offset:272
	s_waitcnt vmcnt(12)
	v_mfma_f32_16x16x32_bf16 v[18:21], v[90:93], v[74:77], v[18:21]
	global_load_dwordx4 v[90:93], v[114:115], off offset:272
	s_waitcnt vmcnt(11)
	v_mfma_f32_16x16x32_bf16 v[30:33], v[78:81], v[74:77], v[30:33]
	global_load_dwordx4 v[78:81], v[118:119], off offset:272
	s_waitcnt vmcnt(11)
	v_mfma_f32_16x16x32_bf16 v[34:37], v[82:85], v[74:77], v[34:37]
	global_load_dwordx4 v[82:85], v[120:121], off offset:272
	s_waitcnt vmcnt(11)
	v_mfma_f32_16x16x32_bf16 v[38:41], v[58:61], v[74:77], v[38:41]
	global_load_dwordx4 v[58:61], v[122:123], off offset:272
	v_mfma_f32_16x16x32_bf16 v[26:29], v[102:105], v[74:77], v[26:29]
	s_waitcnt vmcnt(11)
	v_mfma_f32_16x16x32_bf16 v[42:45], v[86:89], v[74:77], v[42:45]
	global_load_dwordx4 v[86:89], v[106:107], off offset:384
	global_load_dwordx4 v[102:105], v[108:109], off offset:384
	s_waitcnt vmcnt(12)
	v_mfma_f32_16x16x32_bf16 v[46:49], v[50:53], v[74:77], v[46:49]
	global_load_dwordx4 v[50:53], v[110:111], off offset:384
	s_waitcnt vmcnt(12)
	v_mfma_f32_16x16x32_bf16 v[22:25], v[54:57], v[74:77], v[22:25]
	global_load_dwordx4 v[54:57], v[112:113], off offset:384
	global_load_dwordx4 v[74:77], v[116:117], off offset:384
	s_waitcnt vmcnt(12)
	v_mfma_f32_16x16x32_bf16 v[18:21], v[62:65], v[66:69], v[18:21]
	global_load_dwordx4 v[62:65], v[114:115], off offset:384
	s_waitcnt vmcnt(11)
	v_mfma_f32_16x16x32_bf16 v[30:33], v[70:73], v[66:69], v[30:33]
	global_load_dwordx4 v[70:73], v[118:119], off offset:384
	v_mfma_f32_16x16x32_bf16 v[26:29], v[94:97], v[66:69], v[26:29]
	global_load_dwordx4 v[94:97], v[122:123], off offset:384
	s_waitcnt vmcnt(11)
	v_mfma_f32_16x16x32_bf16 v[34:37], v[90:93], v[66:69], v[34:37]
	global_load_dwordx4 v[90:93], v[120:121], off offset:384
	v_mfma_f32_16x16x32_bf16 v[38:41], v[98:101], v[66:69], v[38:41]
	s_waitcnt vmcnt(11)
	v_mfma_f32_16x16x32_bf16 v[42:45], v[78:81], v[66:69], v[42:45]
	global_load_dwordx4 v[78:81], v[106:107], off offset:400
	global_load_dwordx4 v[98:101], v[108:109], off offset:400
	s_waitcnt vmcnt(12)
	v_mfma_f32_16x16x32_bf16 v[46:49], v[82:85], v[66:69], v[46:49]
	global_load_dwordx4 v[82:85], v[110:111], off offset:400
	s_waitcnt vmcnt(12)
	v_mfma_f32_16x16x32_bf16 v[22:25], v[58:61], v[66:69], v[22:25]
	global_load_dwordx4 v[58:61], v[112:113], off offset:400
	global_load_dwordx4 v[66:69], v[114:115], off offset:400
	s_waitcnt vmcnt(11)
	v_mfma_f32_16x16x32_bf16 v[26:29], v[50:53], v[102:105], v[26:29]
	global_load_dwordx4 v[50:53], v[116:117], off offset:400
	s_waitcnt vmcnt(11)
	v_mfma_f32_16x16x32_bf16 v[30:33], v[54:57], v[102:105], v[30:33]
	global_load_dwordx4 v[54:57], v[118:119], off offset:400
	s_waitcnt vmcnt(10)
	v_mfma_f32_16x16x32_bf16 v[34:37], v[62:65], v[102:105], v[34:37]
	global_load_dwordx4 v[62:65], v[120:121], off offset:400
	v_mfma_f32_16x16x32_bf16 v[38:41], v[74:77], v[102:105], v[38:41]
	global_load_dwordx4 v[74:77], v[122:123], off offset:400
	v_mfma_f32_16x16x32_bf16 v[18:21], v[86:89], v[102:105], v[18:21]
	s_waitcnt vmcnt(11)
	v_mfma_f32_16x16x32_bf16 v[42:45], v[70:73], v[102:105], v[42:45]
	v_add_u32_e32 v70, s14, v2
	v_lshrrev_b32_e32 v71, 2, v16
	v_and_or_b32 v70, v71, 12, v70
	v_add_u32_e32 v71, 0xffffc000, v6
	v_cndmask_b32_e32 v73, 0, v7, vcc
	v_cndmask_b32_e32 v72, v71, v6, vcc
	s_waitcnt vmcnt(7)
	v_mfma_f32_16x16x32_bf16 v[18:21], v[78:81], v[98:101], v[18:21]
	v_cndmask_b32_e32 v79, v8, v9, vcc
	v_cndmask_b32_e32 v78, v10, v11, vcc
	v_lshlrev_b64 v[72:73], 12, v[72:73]
	v_lshl_add_u64 v[72:73], v[78:79], 0, v[72:73]
	v_ashrrev_i32_e32 v71, 31, v70
	v_lshl_add_u64 v[72:73], v[70:71], 2, v[72:73]
	s_waitcnt vmcnt(5)
	v_mfma_f32_16x16x32_bf16 v[30:33], v[58:61], v[98:101], v[30:33]
	global_load_dwordx4 v[58:61], v[72:73], off
	v_and_b32_e32 v72, 63, v16
	v_mfma_f32_16x16x32_bf16 v[46:49], v[90:93], v[102:105], v[46:49]
	s_barrier
	v_cmp_lt_i32_e32 vcc, v13, v14
	v_mfma_f32_16x16x32_bf16 v[26:29], v[82:85], v[98:101], v[26:29]
	v_lshlrev_b64 v[6:7], 11, v[6:7]
	v_lshl_add_u64 v[6:7], s[2:3], 0, v[6:7]
	v_lshl_add_u64 v[6:7], v[70:71], 1, v[6:7]
	s_waitcnt vmcnt(5)
	v_mfma_f32_16x16x32_bf16 v[34:37], v[66:69], v[98:101], v[34:37]
	v_lshlrev_b32_e32 v66, 13, v124
	s_waitcnt vmcnt(4)
	v_mfma_f32_16x16x32_bf16 v[38:41], v[50:53], v[98:101], v[38:41]
	v_lshlrev_b32_e32 v50, 4, v72
	v_add3_u32 v50, 0, v66, v50
	ds_write_b128 v50, v[18:21]
	v_mfma_f32_16x16x32_bf16 v[22:25], v[94:97], v[102:105], v[22:25]
	ds_write_b128 v50, v[26:29] offset:1024
	ds_write_b128 v50, v[30:33] offset:2048
	ds_write_b128 v50, v[34:37] offset:3072
	v_lshl_add_u32 v34, v16, 4, 0
	s_waitcnt vmcnt(3)
	v_mfma_f32_16x16x32_bf16 v[18:21], v[54:57], v[98:101], v[42:45]
	s_waitcnt vmcnt(2)
	v_mfma_f32_16x16x32_bf16 v[26:29], v[62:65], v[98:101], v[46:49]
	ds_write_b128 v50, v[38:41] offset:4096
	s_nop 4
	ds_write_b128 v50, v[18:21] offset:5120
	s_nop 0
	ds_write_b128 v50, v[26:29] offset:6144
	s_waitcnt vmcnt(1)
	v_mfma_f32_16x16x32_bf16 v[18:21], v[74:77], v[98:101], v[22:25]
	s_nop 7
	ds_write_b128 v50, v[18:21] offset:7168
	s_waitcnt lgkmcnt(0)
	s_barrier
	ds_read_b128 v[18:21], v34
	ds_read_b128 v[22:25], v34 offset:8192
	ds_read_b128 v[26:29], v34 offset:16384
	s_waitcnt lgkmcnt(2)
	v_pk_add_f32 v[20:21], v[20:21], 0 op_sel_hi:[1,0]
	v_pk_add_f32 v[30:31], v[18:19], 0 op_sel_hi:[1,0]
	s_waitcnt lgkmcnt(1)
	v_pk_add_f32 v[24:25], v[20:21], v[24:25]
	ds_read_b128 v[18:21], v34 offset:24576
	v_pk_add_f32 v[30:31], v[30:31], v[22:23]
	s_waitcnt lgkmcnt(1)
	v_pk_add_f32 v[28:29], v[24:25], v[28:29]
	ds_read_b128 v[22:25], v34 offset:32768
	v_pk_add_f32 v[26:27], v[30:31], v[26:27]
	s_waitcnt lgkmcnt(1)
	v_pk_add_f32 v[28:29], v[28:29], v[20:21]
	v_pk_add_f32 v[30:31], v[26:27], v[18:19]
	ds_read_b128 v[18:21], v34 offset:40960
	s_waitcnt lgkmcnt(1)
	v_pk_add_f32 v[32:33], v[28:29], v[24:25]
	ds_read_b128 v[24:27], v34 offset:49152
	v_pk_add_f32 v[22:23], v[30:31], v[22:23]
	ds_read_b128 v[28:31], v34 offset:57344
	s_waitcnt lgkmcnt(2)
	v_pk_add_f32 v[20:21], v[32:33], v[20:21]
	v_pk_add_f32 v[18:19], v[22:23], v[18:19]
	s_waitcnt lgkmcnt(1)
	v_pk_add_f32 v[20:21], v[20:21], v[26:27]
	v_pk_add_f32 v[18:19], v[18:19], v[24:25]
	s_waitcnt lgkmcnt(0)
	v_pk_add_f32 v[20:21], v[20:21], v[30:31]
	v_pk_add_f32 v[18:19], v[18:19], v[28:29]
	s_waitcnt vmcnt(0)
	v_pk_add_f32 v[20:21], v[60:61], v[20:21]
	v_pk_add_f32 v[18:19], v[58:59], v[18:19]
	s_nop 0
	v_cvt_pk_bf16_f32 v18, v18, v19
	v_cvt_pk_bf16_f32 v19, v20, v21
	global_store_dwordx2 v[6:7], v[18:19], off
	v_and_b32_e32 v21, 0xffff0000, v18
	v_lshlrev_b32_e32 v20, 16, v18
	v_mul_f32_e32 v21, v21, v21
	v_lshlrev_b32_e32 v22, 16, v19
	v_fmac_f32_e32 v21, v20, v20
	v_and_b32_e32 v23, 0xffff0000, v19
	v_fmac_f32_e32 v21, v22, v22
	v_cndmask_b32_e32 v20, v12, v13, vcc
	v_fmac_f32_e32 v21, v23, v23
	v_lshlrev_b32_e32 v20, 2, v20
	ds_bpermute_b32 v20, v20, v21
	v_cmp_lt_i32_e32 vcc, v15, v14
	s_waitcnt lgkmcnt(0)
	s_barrier
	v_cndmask_b32_e32 v7, v12, v15, vcc
	v_add_f32_e32 v6, v21, v20
	v_lshlrev_b32_e32 v7, 2, v7
	ds_bpermute_b32 v7, v7, v6
	v_cmp_gt_u32_e32 vcc, 16, v72
	s_waitcnt lgkmcnt(0)
	s_and_saveexec_b64 s[14:15], vcc
	v_add_f32_e32 v6, v6, v7
	v_lshlrev_b32_e32 v2, 2, v2
	v_lshlrev_b32_e32 v7, 2, v17
	v_add3_u32 v2, 0, v2, v7
	ds_write_b32 v2, v6
	s_or_b64 exec, exec, s[14:15]
	v_cmp_gt_i32_e32 vcc, 16, v16
	s_waitcnt lgkmcnt(0)
	s_barrier
	s_and_saveexec_b64 s[14:15], vcc
	s_cbranch_execz .LBB0_602
	v_lshl_add_u32 v2, v16, 2, 0
	ds_read2_b32 v[6:7], v2 offset1:16
	ds_read2_b32 v[18:19], v2 offset0:32 offset1:48
	ds_read2_b32 v[20:21], v2 offset0:64 offset1:80
	ds_read2_b32 v[22:23], v2 offset0:96 offset1:112
	v_add_u32_e32 v16, s12, v16
	v_ashrrev_i32_e32 v17, 31, v16
	s_lshr_b32 s12, s18, 4
	s_waitcnt lgkmcnt(3)
	v_add_f32_e32 v2, 0, v6
	v_add_f32_e32 v2, v2, v7
	s_waitcnt lgkmcnt(2)
	v_add_f32_e32 v2, v2, v18
	v_add_f32_e32 v2, v2, v19
	s_waitcnt lgkmcnt(1)
	v_add_f32_e32 v2, v2, v20
	v_add_f32_e32 v2, v2, v21
	v_lshlrev_b64 v[6:7], 6, v[16:17]
	s_waitcnt lgkmcnt(0)
	v_add_f32_e32 v2, v2, v22
	v_lshl_add_u64 v[6:7], s[8:9], 0, v[6:7]
	s_and_b32 s12, s12, 56
	v_add_f32_e32 v2, v2, v23
	v_lshl_add_u64 v[6:7], v[6:7], 0, s[12:13]
	global_store_dwordx2 v[6:7], v[2:3], off
	s_branch .LBB0_602

.LBB0_639:
	v_mov_b32_e32 v16, v0
	s_and_b32 s14, s18, 0x380
	s_and_b32 s12, s16, -16
	v_ashrrev_i32_e32 v124, 6, v16
	v_and_b32_e32 v17, 15, v16
	s_waitcnt vmcnt(10)
	v_lshlrev_b32_e32 v18, 8, v124
	v_or_b32_e32 v2, s14, v17
	v_ashrrev_i32_e32 v19, 31, v18
	v_lshlrev_b32_e32 v2, 12, v2
	v_lshl_add_u64 v[20:21], s[6:7], 0, v[2:3]
	v_lshlrev_b64 v[22:23], 1, v[18:19]
	v_lshl_add_u64 v[18:19], v[20:21], 0, v[22:23]
	v_and_b32_e32 v2, 48, v16
	v_lshlrev_b32_e32 v2, 1, v2
	v_lshl_add_u64 v[106:107], v[18:19], 0, v[2:3]
	v_add_co_u32_e32 v110, vcc, s22, v106
	s_addk_i32 s12, 0x4000
	s_nop 0
	v_addc_co_u32_e32 v111, vcc, 0, v107, vcc
	v_add_co_u32_e32 v112, vcc, s23, v106
	v_or_b32_e32 v6, s12, v17
	s_nop 0
	v_addc_co_u32_e32 v113, vcc, 0, v107, vcc
	v_add_co_u32_e32 v114, vcc, s24, v106
	global_load_dwordx4 v[18:21], v[106:107], off
	s_nop 0
	v_addc_co_u32_e32 v115, vcc, 0, v107, vcc
	v_add_co_u32_e32 v116, vcc, s25, v106
	v_mad_i64_i32 v[24:25], s[30:31], v6, s21, v[4:5]
	s_nop 0
	v_addc_co_u32_e32 v117, vcc, 0, v107, vcc
	v_add_co_u32_e32 v118, vcc, s26, v106
	global_load_dwordx4 v[26:29], v[110:111], off
	global_load_dwordx4 v[30:33], v[112:113], off
	v_addc_co_u32_e32 v119, vcc, 0, v107, vcc
	v_add_co_u32_e32 v120, vcc, s27, v106
	v_lshl_add_u64 v[22:23], v[24:25], 0, v[22:23]
	s_nop 0
	v_addc_co_u32_e32 v121, vcc, 0, v107, vcc
	global_load_dwordx4 v[34:37], v[114:115], off
	global_load_dwordx4 v[38:41], v[116:117], off
	global_load_dwordx4 v[42:45], v[118:119], off
	global_load_dwordx4 v[46:49], v[120:121], off
	v_lshl_add_u64 v[108:109], v[22:23], 0, v[2:3]
	global_load_dwordx4 v[22:25], v[108:109], off
	v_add_co_u32_e32 v122, vcc, s28, v106
	v_lshlrev_b32_e32 v2, 4, v124
	s_nop 0
	v_addc_co_u32_e32 v123, vcc, 0, v107, vcc
	global_load_dwordx4 v[50:53], v[122:123], off
	global_load_dwordx4 v[54:57], v[106:107], off offset:16
	global_load_dwordx4 v[58:61], v[108:109], off offset:16
	global_load_dwordx4 v[62:65], v[110:111], off offset:16
	global_load_dwordx4 v[66:69], v[112:113], off offset:16
	global_load_dwordx4 v[70:73], v[114:115], off offset:16
	global_load_dwordx4 v[74:77], v[116:117], off offset:16
	global_load_dwordx4 v[78:81], v[118:119], off offset:16
	global_load_dwordx4 v[82:85], v[120:121], off offset:16
	global_load_dwordx4 v[86:89], v[122:123], off offset:16
	global_load_dwordx4 v[90:93], v[106:107], off offset:128
	global_load_dwordx4 v[94:97], v[108:109], off offset:128
	v_ashrrev_i32_e32 v7, 31, v6
	v_cmp_gt_i32_e32 vcc, s20, v6
	s_waitcnt vmcnt(12)
	v_mfma_f32_16x16x32_bf16 v[18:21], v[18:21], v[22:25], 0
	v_mfma_f32_16x16x32_bf16 v[26:29], v[26:29], v[22:25], 0
	v_mfma_f32_16x16x32_bf16 v[30:33], v[30:33], v[22:25], 0
	v_mfma_f32_16x16x32_bf16 v[34:37], v[34:37], v[22:25], 0
	v_mfma_f32_16x16x32_bf16 v[38:41], v[38:41], v[22:25], 0
	v_mfma_f32_16x16x32_bf16 v[42:45], v[42:45], v[22:25], 0
	v_mfma_f32_16x16x32_bf16 v[46:49], v[46:49], v[22:25], 0
	s_waitcnt vmcnt(11)
	v_mfma_f32_16x16x32_bf16 v[22:25], v[50:53], v[22:25], 0
	global_load_dwordx4 v[50:53], v[110:111], off offset:128
	s_waitcnt vmcnt(10)
	v_mfma_f32_16x16x32_bf16 v[18:21], v[54:57], v[58:61], v[18:21]
	global_load_dwordx4 v[54:57], v[112:113], off offset:128
	s_waitcnt vmcnt(10)
	v_mfma_f32_16x16x32_bf16 v[26:29], v[62:65], v[58:61], v[26:29]
	global_load_dwordx4 v[62:65], v[114:115], off offset:128
	s_waitcnt vmcnt(10)
	v_mfma_f32_16x16x32_bf16 v[30:33], v[66:69], v[58:61], v[30:33]
	global_load_dwordx4 v[66:69], v[116:117], off offset:128
	s_waitcnt vmcnt(10)
	v_mfma_f32_16x16x32_bf16 v[34:37], v[70:73], v[58:61], v[34:37]
	global_load_dwordx4 v[70:73], v[118:119], off offset:128
	s_waitcnt vmcnt(10)
	v_mfma_f32_16x16x32_bf16 v[38:41], v[74:77], v[58:61], v[38:41]
	global_load_dwordx4 v[74:77], v[120:121], off offset:128
	s_waitcnt vmcnt(10)
	v_mfma_f32_16x16x32_bf16 v[42:45], v[78:81], v[58:61], v[42:45]
	global_load_dwordx4 v[78:81], v[122:123], off offset:128
	s_waitcnt vmcnt(10)
	v_mfma_f32_16x16x32_bf16 v[46:49], v[82:85], v[58:61], v[46:49]
	global_load_dwordx4 v[82:85], v[106:107], off offset:144
	global_load_dwordx4 v[98:101], v[108:109], off offset:144
	s_waitcnt vmcnt(11)
	v_mfma_f32_16x16x32_bf16 v[22:25], v[86:89], v[58:61], v[22:25]
	global_load_dwordx4 v[58:61], v[110:111], off offset:144
	global_load_dwordx4 v[86:89], v[112:113], off offset:144
	s_waitcnt vmcnt(10)
	v_mfma_f32_16x16x32_bf16 v[26:29], v[50:53], v[94:97], v[26:29]
	global_load_dwordx4 v[50:53], v[114:115], off offset:144
	s_waitcnt vmcnt(10)
	v_mfma_f32_16x16x32_bf16 v[30:33], v[54:57], v[94:97], v[30:33]
	global_load_dwordx4 v[54:57], v[116:117], off offset:144
	s_waitcnt vmcnt(10)
	v_mfma_f32_16x16x32_bf16 v[34:37], v[62:65], v[94:97], v[34:37]
	global_load_dwordx4 v[62:65], v[118:119], off offset:144
	s_waitcnt vmcnt(10)
	v_mfma_f32_16x16x32_bf16 v[38:41], v[66:69], v[94:97], v[38:41]
	global_load_dwordx4 v[66:69], v[120:121], off offset:144
	v_mfma_f32_16x16x32_bf16 v[18:21], v[90:93], v[94:97], v[18:21]
	s_waitcnt vmcnt(10)
	v_mfma_f32_16x16x32_bf16 v[42:45], v[70:73], v[94:97], v[42:45]
	global_load_dwordx4 v[70:73], v[122:123], off offset:144
	global_load_dwordx4 v[90:93], v[106:107], off offset:256
	s_waitcnt vmcnt(11)
	v_mfma_f32_16x16x32_bf16 v[46:49], v[74:77], v[94:97], v[46:49]
	global_load_dwordx4 v[74:77], v[108:109], off offset:256
	global_load_dwordx4 v[102:105], v[110:111], off offset:256
	s_waitcnt vmcnt(12)
	v_mfma_f32_16x16x32_bf16 v[22:25], v[78:81], v[94:97], v[22:25]
	global_load_dwordx4 v[78:81], v[112:113], off offset:256
	s_waitcnt vmcnt(11)
	v_mfma_f32_16x16x32_bf16 v[18:21], v[82:85], v[98:101], v[18:21]
	global_load_dwordx4 v[82:85], v[114:115], off offset:256
	s_waitcnt vmcnt(11)
	v_mfma_f32_16x16x32_bf16 v[26:29], v[58:61], v[98:101], v[26:29]
	global_load_dwordx4 v[58:61], v[116:117], off offset:256
	s_waitcnt vmcnt(11)
	v_mfma_f32_16x16x32_bf16 v[30:33], v[86:89], v[98:101], v[30:33]
	global_load_dwordx4 v[86:89], v[118:119], off offset:256
	s_waitcnt vmcnt(11)
	v_mfma_f32_16x16x32_bf16 v[34:37], v[50:53], v[98:101], v[34:37]
	global_load_dwordx4 v[50:53], v[120:121], off offset:256
	s_waitcnt vmcnt(11)
	v_mfma_f32_16x16x32_bf16 v[38:41], v[54:57], v[98:101], v[38:41]
	global_load_dwordx4 v[54:57], v[122:123], off offset:256
	s_waitcnt vmcnt(11)
	v_mfma_f32_16x16x32_bf16 v[42:45], v[62:65], v[98:101], v[42:45]
	global_load_dwordx4 v[62:65], v[106:107], off offset:272
	s_waitcnt vmcnt(11)
	v_mfma_f32_16x16x32_bf16 v[46:49], v[66:69], v[98:101], v[46:49]
	global_load_dwordx4 v[66:69], v[108:109], off offset:272
	global_load_dwordx4 v[94:97], v[110:111], off offset:272
	s_waitcnt vmcnt(12)
	v_mfma_f32_16x16x32_bf16 v[22:25], v[70:73], v[98:101], v[22:25]
	global_load_dwordx4 v[70:73], v[112:113], off offset:272
	global_load_dwordx4 v[98:101], v[116:117], off offset:272
	s_waitcnt vmcnt(12)
	v_mfma_f32_16x16x32_bf16 v[18:21], v[90:93], v[74:77], v[18:21]
	global_load_dwordx4 v[90:93], v[114:115], off offset:272
	s_waitcnt vmcnt(11)
	v_mfma_f32_16x16x32_bf16 v[30:33], v[78:81], v[74:77], v[30:33]
	global_load_dwordx4 v[78:81], v[118:119], off offset:272
	s_waitcnt vmcnt(11)
	v_mfma_f32_16x16x32_bf16 v[34:37], v[82:85], v[74:77], v[34:37]
	global_load_dwordx4 v[82:85], v[120:121], off offset:272
	s_waitcnt vmcnt(11)
	v_mfma_f32_16x16x32_bf16 v[38:41], v[58:61], v[74:77], v[38:41]
	global_load_dwordx4 v[58:61], v[122:123], off offset:272
	v_mfma_f32_16x16x32_bf16 v[26:29], v[102:105], v[74:77], v[26:29]
	s_waitcnt vmcnt(11)
	v_mfma_f32_16x16x32_bf16 v[42:45], v[86:89], v[74:77], v[42:45]
	global_load_dwordx4 v[86:89], v[106:107], off offset:384
	global_load_dwordx4 v[102:105], v[108:109], off offset:384
	s_waitcnt vmcnt(12)
	v_mfma_f32_16x16x32_bf16 v[46:49], v[50:53], v[74:77], v[46:49]
	global_load_dwordx4 v[50:53], v[110:111], off offset:384
	s_waitcnt vmcnt(12)
	v_mfma_f32_16x16x32_bf16 v[22:25], v[54:57], v[74:77], v[22:25]
	global_load_dwordx4 v[54:57], v[112:113], off offset:384
	global_load_dwordx4 v[74:77], v[116:117], off offset:384
	s_waitcnt vmcnt(12)
	v_mfma_f32_16x16x32_bf16 v[18:21], v[62:65], v[66:69], v[18:21]
	global_load_dwordx4 v[62:65], v[114:115], off offset:384
	s_waitcnt vmcnt(11)
	v_mfma_f32_16x16x32_bf16 v[30:33], v[70:73], v[66:69], v[30:33]
	global_load_dwordx4 v[70:73], v[118:119], off offset:384
	v_mfma_f32_16x16x32_bf16 v[26:29], v[94:97], v[66:69], v[26:29]
	global_load_dwordx4 v[94:97], v[122:123], off offset:384
	s_waitcnt vmcnt(11)
	v_mfma_f32_16x16x32_bf16 v[34:37], v[90:93], v[66:69], v[34:37]
	global_load_dwordx4 v[90:93], v[120:121], off offset:384
	v_mfma_f32_16x16x32_bf16 v[38:41], v[98:101], v[66:69], v[38:41]
	s_waitcnt vmcnt(11)
	v_mfma_f32_16x16x32_bf16 v[42:45], v[78:81], v[66:69], v[42:45]
	global_load_dwordx4 v[78:81], v[106:107], off offset:400
	global_load_dwordx4 v[98:101], v[108:109], off offset:400
	s_waitcnt vmcnt(12)
	v_mfma_f32_16x16x32_bf16 v[46:49], v[82:85], v[66:69], v[46:49]
	global_load_dwordx4 v[82:85], v[110:111], off offset:400
	s_waitcnt vmcnt(12)
	v_mfma_f32_16x16x32_bf16 v[22:25], v[58:61], v[66:69], v[22:25]
	global_load_dwordx4 v[58:61], v[112:113], off offset:400
	global_load_dwordx4 v[66:69], v[114:115], off offset:400
	s_waitcnt vmcnt(11)
	v_mfma_f32_16x16x32_bf16 v[26:29], v[50:53], v[102:105], v[26:29]
	global_load_dwordx4 v[50:53], v[116:117], off offset:400
	s_waitcnt vmcnt(11)
	v_mfma_f32_16x16x32_bf16 v[30:33], v[54:57], v[102:105], v[30:33]
	global_load_dwordx4 v[54:57], v[118:119], off offset:400
	s_waitcnt vmcnt(10)
	v_mfma_f32_16x16x32_bf16 v[34:37], v[62:65], v[102:105], v[34:37]
	global_load_dwordx4 v[62:65], v[120:121], off offset:400
	v_mfma_f32_16x16x32_bf16 v[38:41], v[74:77], v[102:105], v[38:41]
	global_load_dwordx4 v[74:77], v[122:123], off offset:400
	v_mfma_f32_16x16x32_bf16 v[18:21], v[86:89], v[102:105], v[18:21]
	s_waitcnt vmcnt(11)
	v_mfma_f32_16x16x32_bf16 v[42:45], v[70:73], v[102:105], v[42:45]
	v_add_u32_e32 v70, s14, v2
	v_lshrrev_b32_e32 v71, 2, v16
	v_and_or_b32 v70, v71, 12, v70
	v_add_u32_e32 v71, 0xffffc000, v6
	v_cndmask_b32_e32 v73, 0, v7, vcc
	v_cndmask_b32_e32 v72, v71, v6, vcc
	s_waitcnt vmcnt(7)
	v_mfma_f32_16x16x32_bf16 v[18:21], v[78:81], v[98:101], v[18:21]
	v_cndmask_b32_e32 v79, v8, v9, vcc
	v_cndmask_b32_e32 v78, v10, v11, vcc
	v_lshlrev_b64 v[72:73], 12, v[72:73]
	v_lshl_add_u64 v[72:73], v[78:79], 0, v[72:73]
	v_ashrrev_i32_e32 v71, 31, v70
	v_lshl_add_u64 v[72:73], v[70:71], 2, v[72:73]
	s_waitcnt vmcnt(5)
	v_mfma_f32_16x16x32_bf16 v[30:33], v[58:61], v[98:101], v[30:33]
	global_load_dwordx4 v[58:61], v[72:73], off
	v_and_b32_e32 v72, 63, v16
	v_mfma_f32_16x16x32_bf16 v[46:49], v[90:93], v[102:105], v[46:49]
	s_barrier
	v_cmp_lt_i32_e32 vcc, v13, v14
	v_mfma_f32_16x16x32_bf16 v[26:29], v[82:85], v[98:101], v[26:29]
	v_lshlrev_b64 v[6:7], 11, v[6:7]
	v_lshl_add_u64 v[6:7], s[2:3], 0, v[6:7]
	v_lshl_add_u64 v[6:7], v[70:71], 1, v[6:7]
	s_waitcnt vmcnt(5)
	v_mfma_f32_16x16x32_bf16 v[34:37], v[66:69], v[98:101], v[34:37]
	v_lshlrev_b32_e32 v66, 13, v124
	s_waitcnt vmcnt(4)
	v_mfma_f32_16x16x32_bf16 v[38:41], v[50:53], v[98:101], v[38:41]
	v_lshlrev_b32_e32 v50, 4, v72
	v_add3_u32 v50, 0, v66, v50
	ds_write_b128 v50, v[18:21]
	v_mfma_f32_16x16x32_bf16 v[22:25], v[94:97], v[102:105], v[22:25]
	ds_write_b128 v50, v[26:29] offset:1024
	ds_write_b128 v50, v[30:33] offset:2048
	ds_write_b128 v50, v[34:37] offset:3072
	v_lshl_add_u32 v34, v16, 4, 0
	s_waitcnt vmcnt(3)
	v_mfma_f32_16x16x32_bf16 v[18:21], v[54:57], v[98:101], v[42:45]
	s_waitcnt vmcnt(2)
	v_mfma_f32_16x16x32_bf16 v[26:29], v[62:65], v[98:101], v[46:49]
	ds_write_b128 v50, v[38:41] offset:4096
	s_nop 4
	ds_write_b128 v50, v[18:21] offset:5120
	s_nop 0
	ds_write_b128 v50, v[26:29] offset:6144
	s_waitcnt vmcnt(1)
	v_mfma_f32_16x16x32_bf16 v[18:21], v[74:77], v[98:101], v[22:25]
	s_nop 7
	ds_write_b128 v50, v[18:21] offset:7168
	s_waitcnt lgkmcnt(0)
	s_barrier
	ds_read_b128 v[18:21], v34
	ds_read_b128 v[22:25], v34 offset:8192
	ds_read_b128 v[26:29], v34 offset:16384
	s_waitcnt lgkmcnt(2)
	v_pk_add_f32 v[20:21], v[20:21], 0 op_sel_hi:[1,0]
	v_pk_add_f32 v[30:31], v[18:19], 0 op_sel_hi:[1,0]
	s_waitcnt lgkmcnt(1)
	v_pk_add_f32 v[24:25], v[20:21], v[24:25]
	ds_read_b128 v[18:21], v34 offset:24576
	v_pk_add_f32 v[30:31], v[30:31], v[22:23]
	s_waitcnt lgkmcnt(1)
	v_pk_add_f32 v[28:29], v[24:25], v[28:29]
	ds_read_b128 v[22:25], v34 offset:32768
	v_pk_add_f32 v[26:27], v[30:31], v[26:27]
	s_waitcnt lgkmcnt(1)
	v_pk_add_f32 v[28:29], v[28:29], v[20:21]
	v_pk_add_f32 v[30:31], v[26:27], v[18:19]
	ds_read_b128 v[18:21], v34 offset:40960
	s_waitcnt lgkmcnt(1)
	v_pk_add_f32 v[32:33], v[28:29], v[24:25]
	ds_read_b128 v[24:27], v34 offset:49152
	v_pk_add_f32 v[22:23], v[30:31], v[22:23]
	ds_read_b128 v[28:31], v34 offset:57344
	s_waitcnt lgkmcnt(2)
	v_pk_add_f32 v[20:21], v[32:33], v[20:21]
	v_pk_add_f32 v[18:19], v[22:23], v[18:19]
	s_waitcnt lgkmcnt(1)
	v_pk_add_f32 v[20:21], v[20:21], v[26:27]
	v_pk_add_f32 v[18:19], v[18:19], v[24:25]
	s_waitcnt lgkmcnt(0)
	v_pk_add_f32 v[20:21], v[20:21], v[30:31]
	v_pk_add_f32 v[18:19], v[18:19], v[28:29]
	s_waitcnt vmcnt(0)
	v_pk_add_f32 v[20:21], v[60:61], v[20:21]
	v_pk_add_f32 v[18:19], v[58:59], v[18:19]
	s_nop 0
	v_cvt_pk_bf16_f32 v18, v18, v19
	v_cvt_pk_bf16_f32 v19, v20, v21
	global_store_dwordx2 v[6:7], v[18:19], off
	v_and_b32_e32 v21, 0xffff0000, v18
	v_lshlrev_b32_e32 v20, 16, v18
	v_mul_f32_e32 v21, v21, v21
	v_lshlrev_b32_e32 v22, 16, v19
	v_fmac_f32_e32 v21, v20, v20
	v_and_b32_e32 v23, 0xffff0000, v19
	v_fmac_f32_e32 v21, v22, v22
	v_cndmask_b32_e32 v20, v12, v13, vcc
	v_fmac_f32_e32 v21, v23, v23
	v_lshlrev_b32_e32 v20, 2, v20
	ds_bpermute_b32 v20, v20, v21
	v_cmp_lt_i32_e32 vcc, v15, v14
	s_waitcnt lgkmcnt(0)
	s_barrier
	v_cndmask_b32_e32 v7, v12, v15, vcc
	v_add_f32_e32 v6, v21, v20
	v_lshlrev_b32_e32 v7, 2, v7
	ds_bpermute_b32 v7, v7, v6
	v_cmp_gt_u32_e32 vcc, 16, v72
	s_waitcnt lgkmcnt(0)
	s_and_saveexec_b64 s[14:15], vcc
	v_add_f32_e32 v6, v6, v7
	v_lshlrev_b32_e32 v2, 2, v2
	v_lshlrev_b32_e32 v7, 2, v17
	v_add3_u32 v2, 0, v2, v7
	ds_write_b32 v2, v6
	s_or_b64 exec, exec, s[14:15]
	v_cmp_gt_i32_e32 vcc, 16, v16
	s_waitcnt lgkmcnt(0)
	s_barrier
	s_and_saveexec_b64 s[14:15], vcc
	s_cbranch_execz .LBB0_638
	v_lshl_add_u32 v2, v16, 2, 0
	ds_read2_b32 v[6:7], v2 offset1:16
	ds_read2_b32 v[18:19], v2 offset0:32 offset1:48
	ds_read2_b32 v[20:21], v2 offset0:64 offset1:80
	ds_read2_b32 v[22:23], v2 offset0:96 offset1:112
	v_add_u32_e32 v16, s12, v16
	v_ashrrev_i32_e32 v17, 31, v16
	s_lshr_b32 s12, s18, 4
	s_waitcnt lgkmcnt(3)
	v_add_f32_e32 v2, 0, v6
	v_add_f32_e32 v2, v2, v7
	s_waitcnt lgkmcnt(2)
	v_add_f32_e32 v2, v2, v18
	v_add_f32_e32 v2, v2, v19
	s_waitcnt lgkmcnt(1)
	v_add_f32_e32 v2, v2, v20
	v_add_f32_e32 v2, v2, v21
	v_lshlrev_b64 v[6:7], 6, v[16:17]
	s_waitcnt lgkmcnt(0)
	v_add_f32_e32 v2, v2, v22
	v_lshl_add_u64 v[6:7], s[8:9], 0, v[6:7]
	s_and_b32 s12, s12, 56
	v_add_f32_e32 v2, v2, v23
	v_lshl_add_u64 v[6:7], v[6:7], 0, s[12:13]
	global_store_dwordx2 v[6:7], v[2:3], off
	s_branch .LBB0_638

.LBB0_698:
	v_mov_b32_e32 v11, v0
	s_and_b32 s16, s20, 0x380
	s_and_b32 s14, s18, -16
	v_ashrrev_i32_e32 v13, 6, v11
	v_and_b32_e32 v12, 15, v11
	v_lshlrev_b32_e32 v14, 7, v13
	v_or_b32_e32 v2, s16, v12
	v_ashrrev_i32_e32 v15, 31, v14
	v_lshlrev_b32_e32 v2, 11, v2
	v_lshl_add_u64 v[16:17], s[12:13], 0, v[2:3]
	v_lshlrev_b64 v[14:15], 1, v[14:15]
	v_lshl_add_u64 v[16:17], v[16:17], 0, v[14:15]
	v_and_b32_e32 v2, 48, v11
	v_lshlrev_b32_e32 v2, 1, v2
	s_waitcnt vmcnt(0)
	v_lshl_add_u64 v[100:101], v[16:17], 0, v[2:3]
	v_add_co_u32_e32 v102, vcc, s22, v100
	s_addk_i32 s14, 0x4000
	s_nop 0
	v_addc_co_u32_e32 v103, vcc, 0, v101, vcc
	v_add_co_u32_e32 v104, vcc, s23, v100
	v_or_b32_e32 v4, s14, v12
	s_nop 0
	v_addc_co_u32_e32 v105, vcc, 0, v101, vcc
	v_add_co_u32_e32 v106, vcc, s24, v100
	v_ashrrev_i32_e32 v5, 31, v4
	s_nop 0
	v_addc_co_u32_e32 v107, vcc, 0, v101, vcc
	v_lshlrev_b64 v[110:111], 11, v[4:5]
	v_add_co_u32_e32 v114, vcc, s25, v100
	v_lshl_add_u64 v[112:113], s[2:3], 0, v[110:111]
	s_nop 0
	v_addc_co_u32_e32 v115, vcc, 0, v101, vcc
	v_lshl_add_u64 v[14:15], v[112:113], 0, v[14:15]
	v_add_co_u32_e32 v116, vcc, s26, v100
	v_lshl_add_u64 v[98:99], v[14:15], 0, v[2:3]
	s_nop 0
	v_addc_co_u32_e32 v117, vcc, 0, v101, vcc
	global_load_dwordx4 v[14:17], v[98:99], off
	global_load_dwordx4 v[18:21], v[100:101], off
	global_load_dwordx4 v[22:25], v[102:103], off
	global_load_dwordx4 v[26:29], v[104:105], off
	v_add_co_u32_e32 v118, vcc, s27, v100
	global_load_dwordx4 v[30:33], v[106:107], off
	global_load_dwordx4 v[34:37], v[114:115], off
	v_addc_co_u32_e32 v119, vcc, 0, v101, vcc
	v_add_co_u32_e32 v120, vcc, s28, v100
	global_load_dwordx4 v[38:41], v[116:117], off
	global_load_dwordx4 v[42:45], v[118:119], off
	v_addc_co_u32_e32 v121, vcc, 0, v101, vcc
	global_load_dwordx4 v[46:49], v[120:121], off
	global_load_dwordx4 v[50:53], v[100:101], off offset:16
	global_load_dwordx4 v[54:57], v[98:99], off offset:16
	global_load_dwordx4 v[58:61], v[102:103], off offset:16
	global_load_dwordx4 v[62:65], v[104:105], off offset:16
	global_load_dwordx4 v[66:69], v[106:107], off offset:16
	global_load_dwordx4 v[70:73], v[114:115], off offset:16
	global_load_dwordx4 v[74:77], v[116:117], off offset:16
	global_load_dwordx4 v[78:81], v[118:119], off offset:16
	global_load_dwordx4 v[82:85], v[120:121], off offset:16
	global_load_dwordx4 v[86:89], v[100:101], off offset:128
	global_load_dwordx4 v[90:93], v[98:99], off offset:128
	v_lshlrev_b32_e32 v2, 4, v13
	v_lshlrev_b32_e32 v13, 13, v13
	s_waitcnt vmcnt(18)
	v_mfma_f32_16x16x32_bf16 v[18:21], v[18:21], v[14:17], 0
	s_waitcnt vmcnt(17)
	v_mfma_f32_16x16x32_bf16 v[22:25], v[22:25], v[14:17], 0
	s_waitcnt vmcnt(16)
	v_mfma_f32_16x16x32_bf16 v[26:29], v[26:29], v[14:17], 0
	s_waitcnt vmcnt(15)
	v_mfma_f32_16x16x32_bf16 v[30:33], v[30:33], v[14:17], 0
	s_waitcnt vmcnt(14)
	v_mfma_f32_16x16x32_bf16 v[34:37], v[34:37], v[14:17], 0
	s_waitcnt vmcnt(13)
	v_mfma_f32_16x16x32_bf16 v[38:41], v[38:41], v[14:17], 0
	s_waitcnt vmcnt(12)
	v_mfma_f32_16x16x32_bf16 v[42:45], v[42:45], v[14:17], 0
	s_waitcnt vmcnt(11)
	v_mfma_f32_16x16x32_bf16 v[14:17], v[46:49], v[14:17], 0
	global_load_dwordx4 v[46:49], v[102:103], off offset:128
	s_waitcnt vmcnt(10)
	v_mfma_f32_16x16x32_bf16 v[18:21], v[50:53], v[54:57], v[18:21]
	global_load_dwordx4 v[50:53], v[104:105], off offset:128
	s_waitcnt vmcnt(10)
	v_mfma_f32_16x16x32_bf16 v[22:25], v[58:61], v[54:57], v[22:25]
	global_load_dwordx4 v[58:61], v[106:107], off offset:128
	s_waitcnt vmcnt(10)
	v_mfma_f32_16x16x32_bf16 v[26:29], v[62:65], v[54:57], v[26:29]
	global_load_dwordx4 v[62:65], v[114:115], off offset:128
	s_waitcnt vmcnt(10)
	v_mfma_f32_16x16x32_bf16 v[30:33], v[66:69], v[54:57], v[30:33]
	global_load_dwordx4 v[66:69], v[116:117], off offset:128
	s_waitcnt vmcnt(10)
	v_mfma_f32_16x16x32_bf16 v[34:37], v[70:73], v[54:57], v[34:37]
	global_load_dwordx4 v[70:73], v[118:119], off offset:128
	s_waitcnt vmcnt(10)
	v_mfma_f32_16x16x32_bf16 v[38:41], v[74:77], v[54:57], v[38:41]
	global_load_dwordx4 v[74:77], v[120:121], off offset:128
	s_waitcnt vmcnt(10)
	v_mfma_f32_16x16x32_bf16 v[42:45], v[78:81], v[54:57], v[42:45]
	global_load_dwordx4 v[78:81], v[100:101], off offset:144
	global_load_dwordx4 v[94:97], v[98:99], off offset:144
	v_lshlrev_b64 v[98:99], 6, v[4:5]
	v_lshl_add_u64 v[122:123], s[8:9], 0, v[98:99]
	s_waitcnt vmcnt(11)
	v_mfma_f32_16x16x32_bf16 v[14:17], v[82:85], v[54:57], v[14:17]
	global_load_dwordx4 v[54:57], v[102:103], off offset:144
	global_load_dwordx4 v[82:85], v[104:105], off offset:144
	v_lshlrev_b64 v[4:5], 12, v[4:5]
	s_waitcnt vmcnt(11)
	v_mfma_f32_16x16x32_bf16 v[18:21], v[86:89], v[90:93], v[18:21]
	global_load_dwordx4 v[86:89], v[122:123], off
	v_lshl_add_u64 v[4:5], s[74:75], 0, v[4:5]
	s_waitcnt vmcnt(11)
	v_mfma_f32_16x16x32_bf16 v[22:25], v[46:49], v[90:93], v[22:25]
	global_load_dwordx4 v[46:49], v[106:107], off offset:144
	global_load_dwordx4 v[98:101], v[122:123], off offset:32
	s_waitcnt vmcnt(12)
	v_mfma_f32_16x16x32_bf16 v[26:29], v[50:53], v[90:93], v[26:29]
	global_load_dwordx4 v[50:53], v[114:115], off offset:144
	global_load_dwordx4 v[102:105], v[122:123], off offset:16
	global_load_dwordx4 v[106:109], v[122:123], off offset:48
	v_and_b32_e32 v114, 63, v11
	s_waitcnt vmcnt(14)
	v_mfma_f32_16x16x32_bf16 v[30:33], v[58:61], v[90:93], v[30:33]
	global_load_dwordx4 v[58:61], v[116:117], off offset:144
	s_waitcnt vmcnt(14)
	v_mfma_f32_16x16x32_bf16 v[34:37], v[62:65], v[90:93], v[34:37]
	global_load_dwordx4 v[62:65], v[118:119], off offset:144
	s_waitcnt vmcnt(14)
	v_mfma_f32_16x16x32_bf16 v[38:41], v[66:69], v[90:93], v[38:41]
	global_load_dwordx4 v[66:69], v[120:121], off offset:144
	s_waitcnt vmcnt(14)
	v_mfma_f32_16x16x32_bf16 v[42:45], v[70:73], v[90:93], v[42:45]
	v_add_u32_e32 v70, s16, v2
	v_lshrrev_b32_e32 v71, 2, v11
	v_and_or_b32 v70, v71, 12, v70
	v_ashrrev_i32_e32 v71, 31, v70
	v_lshlrev_b64 v[72:73], 1, v[70:71]
	s_waitcnt vmcnt(13)
	v_mfma_f32_16x16x32_bf16 v[14:17], v[74:77], v[90:93], v[14:17]
	v_lshl_add_u64 v[74:75], v[112:113], 0, v[72:73]
	v_lshl_add_u64 v[76:77], s[10:11], 0, v[110:111]
	v_lshl_add_u64 v[72:73], v[76:77], 0, v[72:73]
	s_waitcnt vmcnt(10)
	v_mfma_f32_16x16x32_bf16 v[22:25], v[54:57], v[94:97], v[22:25]
	global_load_dwordx2 v[54:55], v[74:75], off
	global_load_dwordx2 v[56:57], v[72:73], off
	s_waitcnt vmcnt(10)
	v_mov_b32_e32 v72, v88
	v_mfma_f32_16x16x32_bf16 v[18:21], v[78:81], v[94:97], v[18:21]
	s_barrier
	v_lshl_add_u64 v[4:5], v[70:71], 2, v[4:5]
	v_mfma_f32_16x16x32_bf16 v[26:29], v[82:85], v[94:97], v[26:29]
	s_waitcnt vmcnt(8)
	v_mov_b32_e32 v73, v100
	v_mfma_f32_16x16x32_bf16 v[30:33], v[46:49], v[94:97], v[30:33]
	v_mov_b32_e32 v100, v89
	s_waitcnt vmcnt(6)
	v_mov_b32_e32 v46, v102
	s_waitcnt vmcnt(5)
	v_mov_b32_e32 v47, v106
	v_mov_b32_e32 v106, v103
	v_mfma_f32_16x16x32_bf16 v[34:37], v[50:53], v[94:97], v[34:37]
	v_mov_b32_e32 v48, v104
	v_mov_b32_e32 v49, v108
	v_mov_b32_e32 v108, v105
	v_lshlrev_b32_e32 v50, 4, v114
	v_pk_add_f32 v[46:47], v[46:47], v[106:107]
	v_pk_add_f32 v[48:49], v[48:49], v[108:109]
	v_add3_u32 v13, 0, v13, v50
	s_waitcnt vmcnt(4)
	v_mfma_f32_16x16x32_bf16 v[38:41], v[58:61], v[94:97], v[38:41]
	v_add_f32_e64 v46, v46, v48
	v_add_f32_e64 v47, v47, v49
	v_mov_b32_e32 v48, v86
	v_mov_b32_e32 v49, v98
	s_waitcnt vmcnt(3)
	v_mfma_f32_16x16x32_bf16 v[42:45], v[62:65], v[94:97], v[42:45]
	v_mov_b32_e32 v98, v87
	v_pk_add_f32 v[72:73], v[72:73], v[100:101]
	s_waitcnt vmcnt(2)
	v_mfma_f32_16x16x32_bf16 v[14:17], v[66:69], v[94:97], v[14:17]
	ds_write_b128 v13, v[18:21]
	ds_write_b128 v13, v[22:25] offset:1024
	ds_write_b128 v13, v[26:29] offset:2048
	ds_write_b128 v13, v[30:33] offset:3072
	ds_write_b128 v13, v[34:37] offset:4096
	ds_write_b128 v13, v[38:41] offset:5120
	ds_write_b128 v13, v[42:45] offset:6144
	s_nop 0
	ds_write_b128 v13, v[14:17] offset:7168
	v_lshl_add_u32 v13, v11, 4, 0
	s_waitcnt lgkmcnt(0)
	s_barrier
	ds_read_b128 v[14:17], v13
	v_pk_add_f32 v[18:19], v[48:49], v[98:99]
	s_nop 0
	v_pk_add_f32 v[22:23], v[18:19], v[72:73]
	ds_read_b128 v[18:21], v13 offset:8192
	v_pk_add_f32 v[26:27], v[22:23], v[46:47]
	ds_read_b128 v[22:25], v13 offset:16384
	s_waitcnt lgkmcnt(2)
	v_pk_add_f32 v[16:17], v[16:17], 0 op_sel_hi:[1,0]
	v_pk_add_f32 v[14:15], v[14:15], 0 op_sel_hi:[1,0]
	s_waitcnt lgkmcnt(1)
	v_pk_add_f32 v[20:21], v[16:17], v[20:21]
	v_pk_add_f32 v[28:29], v[14:15], v[18:19]
	ds_read_b128 v[14:17], v13 offset:24576
	s_waitcnt lgkmcnt(1)
	v_pk_add_f32 v[30:31], v[20:21], v[24:25]
	ds_read_b128 v[18:21], v13 offset:32768
	v_pk_add_f32 v[28:29], v[28:29], v[22:23]
	ds_read_b128 v[22:25], v13 offset:40960
	s_waitcnt lgkmcnt(2)
	v_pk_add_f32 v[16:17], v[30:31], v[16:17]
	v_pk_add_f32 v[14:15], v[28:29], v[14:15]
	s_waitcnt lgkmcnt(1)
	v_pk_add_f32 v[16:17], v[16:17], v[20:21]
	v_pk_add_f32 v[14:15], v[14:15], v[18:19]
	s_waitcnt lgkmcnt(0)
	v_pk_add_f32 v[24:25], v[16:17], v[24:25]
	v_pk_add_f32 v[22:23], v[14:15], v[22:23]
	ds_read_b128 v[14:17], v13 offset:49152
	ds_read_b128 v[18:21], v13 offset:57344
	v_add_f32_e32 v13, v26, v27
	v_fmamk_f32 v13, v13, 0x3a800000, v6
	v_mul_f32_e32 v26, 0x4b800000, v13
	v_cmp_gt_f32_e32 vcc, s29, v13
	s_waitcnt lgkmcnt(1)
	v_pk_add_f32 v[14:15], v[22:23], v[14:15]
	v_pk_add_f32 v[16:17], v[24:25], v[16:17]
	v_cndmask_b32_e32 v13, v13, v26, vcc
	v_rsq_f32_e32 v13, v13
	s_waitcnt lgkmcnt(0)
	v_pk_add_f32 v[14:15], v[14:15], v[18:19]
	v_mul_f32_e32 v18, 0x45800000, v13
	v_cndmask_b32_e32 v13, v13, v18, vcc
	v_mul_f32_e32 v14, v13, v14
	v_mul_f32_e32 v14, 0xbfb8aa3b, v14
	v_exp_f32_e32 v18, v14
	v_mul_f32_e32 v14, v13, v15
	v_mul_f32_e32 v14, 0xbfb8aa3b, v14
	v_exp_f32_e32 v19, v14
	v_pk_add_f32 v[14:15], v[16:17], v[20:21]
	v_add_f32_e32 v16, 1.0, v18
	v_mul_f32_e32 v14, v13, v14
	v_mul_f32_e32 v13, v13, v15
	v_add_f32_e32 v17, 1.0, v19
	v_mul_f32_e32 v14, 0xbfb8aa3b, v14
	v_mul_f32_e32 v13, 0xbfb8aa3b, v13
	v_rcp_f32_e32 v16, v16
	v_rcp_f32_e32 v17, v17
	v_exp_f32_e32 v22, v14
	v_exp_f32_e32 v13, v13
	s_waitcnt vmcnt(1)
	v_lshlrev_b32_e32 v18, 16, v54
	v_and_b32_e32 v19, 0xffff0000, v54
	s_waitcnt vmcnt(0)
	v_lshlrev_b32_e32 v20, 16, v56
	v_and_b32_e32 v21, 0xffff0000, v56
	v_pk_fma_f32 v[14:15], v[16:17], v[20:21], v[18:19]
	v_add_f32_e32 v16, 1.0, v22
	v_add_f32_e32 v13, 1.0, v13
	v_rcp_f32_e32 v16, v16
	v_rcp_f32_e32 v17, v13
	v_lshlrev_b32_e32 v18, 16, v55
	v_and_b32_e32 v19, 0xffff0000, v55
	v_lshlrev_b32_e32 v20, 16, v57
	v_and_b32_e32 v21, 0xffff0000, v57
	v_pk_fma_f32 v[16:17], v[16:17], v[20:21], v[18:19]
	v_pk_mul_f32 v[18:19], v[14:15], v[14:15]
	v_pk_mul_f32 v[20:21], v[16:17], v[16:17]
	v_add_f32_e32 v13, v18, v19
	v_cmp_lt_i32_e32 vcc, v8, v9
	v_add_f32_e32 v13, v20, v13
	v_add_f32_e32 v13, v21, v13
	v_cndmask_b32_e32 v18, v7, v8, vcc
	v_lshlrev_b32_e32 v18, 2, v18
	ds_bpermute_b32 v18, v18, v13
	v_cmp_lt_i32_e32 vcc, v10, v9
	global_store_dwordx4 v[4:5], v[14:17], off
	s_waitcnt lgkmcnt(0)
	v_cndmask_b32_e32 v5, v7, v10, vcc
	v_add_f32_e32 v4, v13, v18
	v_lshlrev_b32_e32 v5, 2, v5
	ds_bpermute_b32 v5, v5, v4
	v_cmp_gt_u32_e32 vcc, 16, v114
	s_barrier
	s_waitcnt lgkmcnt(0)
	s_and_saveexec_b64 s[16:17], vcc
	v_add_f32_e32 v4, v4, v5
	v_lshlrev_b32_e32 v2, 2, v2
	v_lshlrev_b32_e32 v5, 2, v12
	v_add3_u32 v2, 0, v2, v5
	ds_write_b32 v2, v4
	s_or_b64 exec, exec, s[16:17]
	v_cmp_gt_i32_e32 vcc, 16, v11
	s_waitcnt lgkmcnt(0)
	s_barrier
	s_and_saveexec_b64 s[16:17], vcc
	s_cbranch_execz .LBB0_697
	v_lshl_add_u32 v2, v11, 2, 0
	ds_read2_b32 v[4:5], v2 offset1:16
	ds_read2_b32 v[14:15], v2 offset0:32 offset1:48
	ds_read2_b32 v[16:17], v2 offset0:64 offset1:80
	ds_read2_b32 v[18:19], v2 offset0:96 offset1:112
	v_add_u32_e32 v12, s14, v11
	v_ashrrev_i32_e32 v13, 31, v12
	s_lshr_b32 s14, s20, 4
	s_waitcnt lgkmcnt(3)
	v_add_f32_e32 v2, 0, v4
	v_add_f32_e32 v2, v2, v5
	s_waitcnt lgkmcnt(2)
	v_add_f32_e32 v2, v2, v14
	v_add_f32_e32 v2, v2, v15
	s_waitcnt lgkmcnt(1)
	v_add_f32_e32 v2, v2, v16
	v_add_f32_e32 v2, v2, v17
	v_lshlrev_b64 v[4:5], 6, v[12:13]
	s_waitcnt lgkmcnt(0)
	v_add_f32_e32 v2, v2, v18
	v_lshl_add_u64 v[4:5], s[6:7], 0, v[4:5]
	s_and_b32 s14, s14, 56
	v_add_f32_e32 v2, v2, v19
	v_lshl_add_u64 v[4:5], v[4:5], 0, s[14:15]
	global_store_dwordx2 v[4:5], v[2:3], off
	s_branch .LBB0_697

.LBB0_734:
	v_mov_b32_e32 v10, v0
	s_and_b32 s12, s16, 0x380
	s_and_b32 s4, s14, -16
	v_ashrrev_i32_e32 v122, 6, v10
	v_and_b32_e32 v11, 15, v10
	v_lshlrev_b32_e32 v12, 7, v122
	v_or_b32_e32 v2, s12, v11
	v_ashrrev_i32_e32 v13, 31, v12
	v_lshlrev_b32_e32 v2, 11, v2
	v_lshl_add_u64 v[14:15], s[0:1], 0, v[2:3]
	v_lshlrev_b64 v[12:13], 1, v[12:13]
	v_lshl_add_u64 v[14:15], v[14:15], 0, v[12:13]
	v_and_b32_e32 v2, 48, v10
	v_lshlrev_b32_e32 v2, 1, v2
	v_lshl_add_u64 v[98:99], v[14:15], 0, v[2:3]
	s_waitcnt vmcnt(0)
	v_add_co_u32_e32 v100, vcc, s18, v98
	s_addk_i32 s4, 0x4000
	s_nop 0
	v_addc_co_u32_e32 v101, vcc, 0, v99, vcc
	v_add_co_u32_e32 v102, vcc, s19, v98
	v_or_b32_e32 v4, s4, v11
	s_nop 0
	v_addc_co_u32_e32 v103, vcc, 0, v99, vcc
	v_add_co_u32_e32 v104, vcc, s20, v98
	v_ashrrev_i32_e32 v5, 31, v4
	s_nop 0
	v_addc_co_u32_e32 v105, vcc, 0, v99, vcc
	v_lshlrev_b64 v[108:109], 11, v[4:5]
	v_add_co_u32_e32 v112, vcc, s21, v98
	v_lshl_add_u64 v[110:111], s[2:3], 0, v[108:109]
	s_nop 0
	v_addc_co_u32_e32 v113, vcc, 0, v99, vcc
	v_lshl_add_u64 v[12:13], v[110:111], 0, v[12:13]
	v_add_co_u32_e32 v114, vcc, s22, v98
	v_lshl_add_u64 v[96:97], v[12:13], 0, v[2:3]
	s_nop 0
	v_addc_co_u32_e32 v115, vcc, 0, v99, vcc
	global_load_dwordx4 v[12:15], v[96:97], off
	global_load_dwordx4 v[16:19], v[98:99], off
	global_load_dwordx4 v[20:23], v[100:101], off
	global_load_dwordx4 v[24:27], v[102:103], off
	v_add_co_u32_e32 v116, vcc, s23, v98
	global_load_dwordx4 v[28:31], v[104:105], off
	global_load_dwordx4 v[32:35], v[112:113], off
	v_addc_co_u32_e32 v117, vcc, 0, v99, vcc
	v_add_co_u32_e32 v118, vcc, s24, v98
	global_load_dwordx4 v[36:39], v[114:115], off
	global_load_dwordx4 v[40:43], v[116:117], off
	v_addc_co_u32_e32 v119, vcc, 0, v99, vcc
	global_load_dwordx4 v[44:47], v[118:119], off
	global_load_dwordx4 v[48:51], v[98:99], off offset:16
	global_load_dwordx4 v[52:55], v[96:97], off offset:16
	global_load_dwordx4 v[56:59], v[100:101], off offset:16
	global_load_dwordx4 v[60:63], v[102:103], off offset:16
	global_load_dwordx4 v[64:67], v[104:105], off offset:16
	global_load_dwordx4 v[68:71], v[112:113], off offset:16
	global_load_dwordx4 v[72:75], v[114:115], off offset:16
	global_load_dwordx4 v[76:79], v[116:117], off offset:16
	global_load_dwordx4 v[80:83], v[118:119], off offset:16
	global_load_dwordx4 v[84:87], v[98:99], off offset:128
	global_load_dwordx4 v[88:91], v[96:97], off offset:128
	v_lshlrev_b32_e32 v2, 4, v122
	s_waitcnt vmcnt(18)
	v_mfma_f32_16x16x32_bf16 v[16:19], v[16:19], v[12:15], 0
	s_waitcnt vmcnt(17)
	v_mfma_f32_16x16x32_bf16 v[20:23], v[20:23], v[12:15], 0
	s_waitcnt vmcnt(16)
	v_mfma_f32_16x16x32_bf16 v[24:27], v[24:27], v[12:15], 0
	s_waitcnt vmcnt(15)
	v_mfma_f32_16x16x32_bf16 v[28:31], v[28:31], v[12:15], 0
	s_waitcnt vmcnt(14)
	v_mfma_f32_16x16x32_bf16 v[32:35], v[32:35], v[12:15], 0
	s_waitcnt vmcnt(13)
	v_mfma_f32_16x16x32_bf16 v[36:39], v[36:39], v[12:15], 0
	s_waitcnt vmcnt(12)
	v_mfma_f32_16x16x32_bf16 v[40:43], v[40:43], v[12:15], 0
	s_waitcnt vmcnt(11)
	v_mfma_f32_16x16x32_bf16 v[12:15], v[44:47], v[12:15], 0
	global_load_dwordx4 v[44:47], v[100:101], off offset:128
	s_waitcnt vmcnt(10)
	v_mfma_f32_16x16x32_bf16 v[16:19], v[48:51], v[52:55], v[16:19]
	global_load_dwordx4 v[48:51], v[102:103], off offset:128
	s_waitcnt vmcnt(10)
	v_mfma_f32_16x16x32_bf16 v[20:23], v[56:59], v[52:55], v[20:23]
	global_load_dwordx4 v[56:59], v[104:105], off offset:128
	s_waitcnt vmcnt(10)
	v_mfma_f32_16x16x32_bf16 v[24:27], v[60:63], v[52:55], v[24:27]
	global_load_dwordx4 v[60:63], v[112:113], off offset:128
	s_waitcnt vmcnt(10)
	v_mfma_f32_16x16x32_bf16 v[28:31], v[64:67], v[52:55], v[28:31]
	global_load_dwordx4 v[64:67], v[114:115], off offset:128
	s_waitcnt vmcnt(10)
	v_mfma_f32_16x16x32_bf16 v[32:35], v[68:71], v[52:55], v[32:35]
	global_load_dwordx4 v[68:71], v[116:117], off offset:128
	s_waitcnt vmcnt(10)
	v_mfma_f32_16x16x32_bf16 v[36:39], v[72:75], v[52:55], v[36:39]
	global_load_dwordx4 v[72:75], v[118:119], off offset:128
	s_waitcnt vmcnt(10)
	v_mfma_f32_16x16x32_bf16 v[40:43], v[76:79], v[52:55], v[40:43]
	global_load_dwordx4 v[76:79], v[98:99], off offset:144
	global_load_dwordx4 v[92:95], v[96:97], off offset:144
	v_lshlrev_b64 v[96:97], 6, v[4:5]
	v_lshl_add_u64 v[120:121], s[8:9], 0, v[96:97]
	s_waitcnt vmcnt(11)
	v_mfma_f32_16x16x32_bf16 v[12:15], v[80:83], v[52:55], v[12:15]
	global_load_dwordx4 v[52:55], v[100:101], off offset:144
	global_load_dwordx4 v[80:83], v[102:103], off offset:144
	v_lshlrev_b64 v[4:5], 12, v[4:5]
	s_waitcnt vmcnt(11)
	v_mfma_f32_16x16x32_bf16 v[16:19], v[84:87], v[88:91], v[16:19]
	global_load_dwordx4 v[84:87], v[120:121], off
	v_lshl_add_u64 v[4:5], s[74:75], 0, v[4:5]
	s_waitcnt vmcnt(11)
	v_mfma_f32_16x16x32_bf16 v[20:23], v[44:47], v[88:91], v[20:23]
	global_load_dwordx4 v[44:47], v[104:105], off offset:144
	global_load_dwordx4 v[96:99], v[120:121], off offset:32
	s_waitcnt vmcnt(12)
	v_mfma_f32_16x16x32_bf16 v[24:27], v[48:51], v[88:91], v[24:27]
	global_load_dwordx4 v[48:51], v[112:113], off offset:144
	global_load_dwordx4 v[100:103], v[120:121], off offset:16
	global_load_dwordx4 v[104:107], v[120:121], off offset:48
	v_and_b32_e32 v112, 63, v10
	s_waitcnt vmcnt(14)
	v_mfma_f32_16x16x32_bf16 v[28:31], v[56:59], v[88:91], v[28:31]
	global_load_dwordx4 v[56:59], v[114:115], off offset:144
	s_waitcnt vmcnt(14)
	v_mfma_f32_16x16x32_bf16 v[32:35], v[60:63], v[88:91], v[32:35]
	global_load_dwordx4 v[60:63], v[116:117], off offset:144
	s_waitcnt vmcnt(14)
	v_mfma_f32_16x16x32_bf16 v[36:39], v[64:67], v[88:91], v[36:39]
	global_load_dwordx4 v[64:67], v[118:119], off offset:144
	s_waitcnt vmcnt(14)
	v_mfma_f32_16x16x32_bf16 v[40:43], v[68:71], v[88:91], v[40:43]
	v_add_u32_e32 v68, s12, v2
	v_lshrrev_b32_e32 v69, 2, v10
	v_and_or_b32 v68, v69, 12, v68
	v_ashrrev_i32_e32 v69, 31, v68
	v_lshlrev_b64 v[70:71], 1, v[68:69]
	s_waitcnt vmcnt(13)
	v_mfma_f32_16x16x32_bf16 v[12:15], v[72:75], v[88:91], v[12:15]
	v_lshl_add_u64 v[72:73], v[110:111], 0, v[70:71]
	v_lshl_add_u64 v[74:75], s[10:11], 0, v[108:109]
	v_lshl_add_u64 v[70:71], v[74:75], 0, v[70:71]
	s_waitcnt vmcnt(10)
	v_mfma_f32_16x16x32_bf16 v[20:23], v[52:55], v[92:95], v[20:23]
	global_load_dwordx2 v[52:53], v[72:73], off
	global_load_dwordx2 v[54:55], v[70:71], off
	s_waitcnt vmcnt(10)
	v_mov_b32_e32 v70, v86
	v_mfma_f32_16x16x32_bf16 v[16:19], v[76:79], v[92:95], v[16:19]
	s_barrier
	v_lshl_add_u64 v[4:5], v[68:69], 2, v[4:5]
	v_mfma_f32_16x16x32_bf16 v[24:27], v[80:83], v[92:95], v[24:27]
	s_waitcnt vmcnt(8)
	v_mov_b32_e32 v71, v98
	v_mfma_f32_16x16x32_bf16 v[28:31], v[44:47], v[92:95], v[28:31]
	v_mov_b32_e32 v98, v87
	s_waitcnt vmcnt(6)
	v_mov_b32_e32 v44, v100
	s_waitcnt vmcnt(5)
	v_mov_b32_e32 v45, v104
	v_mov_b32_e32 v104, v101
	v_mfma_f32_16x16x32_bf16 v[32:35], v[48:51], v[92:95], v[32:35]
	v_mov_b32_e32 v46, v102
	v_mov_b32_e32 v47, v106
	v_mov_b32_e32 v106, v103
	v_lshlrev_b32_e32 v48, 13, v122
	v_lshlrev_b32_e32 v49, 4, v112
	v_pk_add_f32 v[44:45], v[44:45], v[104:105]
	v_pk_add_f32 v[46:47], v[46:47], v[106:107]
	v_add3_u32 v48, 0, v48, v49
	s_waitcnt vmcnt(4)
	v_mfma_f32_16x16x32_bf16 v[36:39], v[56:59], v[92:95], v[36:39]
	v_add_f32_e64 v44, v44, v46
	v_add_f32_e64 v45, v45, v47
	v_mov_b32_e32 v46, v84
	v_mov_b32_e32 v47, v96
	s_waitcnt vmcnt(3)
	v_mfma_f32_16x16x32_bf16 v[40:43], v[60:63], v[92:95], v[40:43]
	v_mov_b32_e32 v96, v85
	v_pk_add_f32 v[70:71], v[70:71], v[98:99]
	s_waitcnt vmcnt(2)
	v_mfma_f32_16x16x32_bf16 v[12:15], v[64:67], v[92:95], v[12:15]
	ds_write_b128 v48, v[16:19]
	ds_write_b128 v48, v[20:23] offset:1024
	ds_write_b128 v48, v[24:27] offset:2048
	ds_write_b128 v48, v[28:31] offset:3072
	ds_write_b128 v48, v[32:35] offset:4096
	ds_write_b128 v48, v[36:39] offset:5120
	ds_write_b128 v48, v[40:43] offset:6144
	s_nop 0
	ds_write_b128 v48, v[12:15] offset:7168
	v_lshl_add_u32 v30, v10, 4, 0
	s_waitcnt lgkmcnt(0)
	s_barrier
	ds_read_b128 v[12:15], v30
	v_pk_add_f32 v[16:17], v[46:47], v[96:97]
	s_nop 0
	v_pk_add_f32 v[20:21], v[16:17], v[70:71]
	ds_read_b128 v[16:19], v30 offset:8192
	v_pk_add_f32 v[24:25], v[20:21], v[44:45]
	ds_read_b128 v[20:23], v30 offset:16384
	s_waitcnt lgkmcnt(2)
	v_pk_add_f32 v[14:15], v[14:15], 0 op_sel_hi:[1,0]
	v_pk_add_f32 v[12:13], v[12:13], 0 op_sel_hi:[1,0]
	s_waitcnt lgkmcnt(1)
	v_pk_add_f32 v[18:19], v[14:15], v[18:19]
	v_pk_add_f32 v[26:27], v[12:13], v[16:17]
	ds_read_b128 v[12:15], v30 offset:24576
	s_waitcnt lgkmcnt(1)
	v_pk_add_f32 v[28:29], v[18:19], v[22:23]
	ds_read_b128 v[16:19], v30 offset:32768
	v_pk_add_f32 v[26:27], v[26:27], v[20:21]
	ds_read_b128 v[20:23], v30 offset:40960
	v_add_f32_e32 v24, v24, v25
	s_waitcnt lgkmcnt(2)
	v_pk_add_f32 v[14:15], v[28:29], v[14:15]
	v_pk_add_f32 v[12:13], v[26:27], v[12:13]
	v_fmamk_f32 v24, v24, 0x3a800000, v6
	s_waitcnt lgkmcnt(1)
	v_pk_add_f32 v[14:15], v[14:15], v[18:19]
	v_pk_add_f32 v[12:13], v[12:13], v[16:17]
	v_mul_f32_e32 v25, 0x4b800000, v24
	v_cmp_gt_f32_e32 vcc, s25, v24
	s_waitcnt lgkmcnt(0)
	v_pk_add_f32 v[22:23], v[14:15], v[22:23]
	v_pk_add_f32 v[20:21], v[12:13], v[20:21]
	ds_read_b128 v[12:15], v30 offset:49152
	ds_read_b128 v[16:19], v30 offset:57344
	v_cndmask_b32_e32 v24, v24, v25, vcc
	v_rsq_f32_e32 v24, v24
	s_waitcnt lgkmcnt(1)
	v_pk_add_f32 v[12:13], v[20:21], v[12:13]
	s_waitcnt lgkmcnt(0)
	v_pk_add_f32 v[12:13], v[12:13], v[16:17]
	v_mul_f32_e32 v16, 0x45800000, v24
	v_cndmask_b32_e32 v20, v24, v16, vcc
	v_mul_f32_e32 v12, v20, v12
	v_mul_f32_e32 v12, 0xbfb8aa3b, v12
	v_exp_f32_e32 v16, v12
	v_mul_f32_e32 v12, v20, v13
	v_pk_add_f32 v[14:15], v[22:23], v[14:15]
	v_mul_f32_e32 v12, 0xbfb8aa3b, v12
	v_exp_f32_e32 v17, v12
	v_pk_add_f32 v[12:13], v[14:15], v[18:19]
	v_add_f32_e32 v14, 1.0, v16
	v_mul_f32_e32 v12, v20, v12
	v_mul_f32_e32 v12, 0xbfb8aa3b, v12
	v_exp_f32_e32 v21, v12
	v_mul_f32_e32 v12, v20, v13
	v_add_f32_e32 v15, 1.0, v17
	v_mul_f32_e32 v12, 0xbfb8aa3b, v12
	v_rcp_f32_e32 v14, v14
	v_rcp_f32_e32 v15, v15
	v_exp_f32_e32 v20, v12
	s_waitcnt vmcnt(1)
	v_lshlrev_b32_e32 v16, 16, v52
	v_and_b32_e32 v17, 0xffff0000, v52
	s_waitcnt vmcnt(0)
	v_lshlrev_b32_e32 v18, 16, v54
	v_and_b32_e32 v19, 0xffff0000, v54
	v_pk_fma_f32 v[12:13], v[14:15], v[18:19], v[16:17]
	v_add_f32_e32 v14, 1.0, v21
	v_add_f32_e32 v15, 1.0, v20
	v_rcp_f32_e32 v14, v14
	v_rcp_f32_e32 v15, v15
	v_lshlrev_b32_e32 v16, 16, v53
	v_and_b32_e32 v17, 0xffff0000, v53
	v_lshlrev_b32_e32 v18, 16, v55
	v_and_b32_e32 v19, 0xffff0000, v55
	v_pk_fma_f32 v[14:15], v[14:15], v[18:19], v[16:17]
	v_pk_mul_f32 v[16:17], v[12:13], v[12:13]
	v_pk_mul_f32 v[18:19], v[14:15], v[14:15]
	v_add_f32_e32 v16, v16, v17
	v_cmp_lt_i32_e32 vcc, v7, v8
	v_add_f32_e32 v16, v18, v16
	v_add_f32_e32 v16, v19, v16
	v_cndmask_b32_e32 v17, v1, v7, vcc
	v_lshlrev_b32_e32 v17, 2, v17
	ds_bpermute_b32 v17, v17, v16
	v_cmp_lt_i32_e32 vcc, v9, v8
	global_store_dwordx4 v[4:5], v[12:15], off
	s_waitcnt lgkmcnt(0)
	v_cndmask_b32_e32 v5, v1, v9, vcc
	v_add_f32_e32 v4, v16, v17
	v_lshlrev_b32_e32 v5, 2, v5
	ds_bpermute_b32 v5, v5, v4
	v_cmp_gt_u32_e32 vcc, 16, v112
	s_barrier
	s_waitcnt lgkmcnt(0)
	s_and_saveexec_b64 s[12:13], vcc
	v_add_f32_e32 v4, v4, v5
	v_lshlrev_b32_e32 v2, 2, v2
	v_lshlrev_b32_e32 v5, 2, v11
	v_add3_u32 v2, 0, v2, v5
	ds_write_b32 v2, v4
	s_or_b64 exec, exec, s[12:13]
	v_cmp_gt_i32_e32 vcc, 16, v10
	s_waitcnt lgkmcnt(0)
	s_barrier
	s_and_saveexec_b64 s[12:13], vcc
	s_cbranch_execz .LBB0_733
	v_lshl_add_u32 v2, v10, 2, 0
	ds_read2_b32 v[4:5], v2 offset1:16
	ds_read2_b32 v[12:13], v2 offset0:32 offset1:48
	ds_read2_b32 v[14:15], v2 offset0:64 offset1:80
	ds_read2_b32 v[16:17], v2 offset0:96 offset1:112
	v_add_u32_e32 v10, s4, v10
	v_ashrrev_i32_e32 v11, 31, v10
	s_lshr_b32 s4, s16, 4
	s_waitcnt lgkmcnt(3)
	v_add_f32_e32 v2, 0, v4
	v_add_f32_e32 v2, v2, v5
	s_waitcnt lgkmcnt(2)
	v_add_f32_e32 v2, v2, v12
	v_add_f32_e32 v2, v2, v13
	s_waitcnt lgkmcnt(1)
	v_add_f32_e32 v2, v2, v14
	v_add_f32_e32 v2, v2, v15
	v_lshlrev_b64 v[4:5], 6, v[10:11]
	s_waitcnt lgkmcnt(0)
	v_add_f32_e32 v2, v2, v16
	v_lshl_add_u64 v[4:5], s[6:7], 0, v[4:5]
	s_and_b32 s4, s4, 56
	v_add_f32_e32 v2, v2, v17
	v_lshl_add_u64 v[4:5], v[4:5], 0, s[4:5]
	global_store_dwordx2 v[4:5], v[2:3], off
	s_branch .LBB0_733
